# GEMM K-loops: the loop-top scalar address block (7 SALU) moved out of the heaviest load section (phase 1) to the start of phase 2's load section
# speedup vs baseline: 1.0088x; 1.0001x over previous
.LBB0_197:
	ds_read_b128 v[144:147], v151
	ds_read_b128 v[154:157], v151 offset:1024
	ds_read_b128 v[158:161], v151 offset:2048
	ds_read_b128 v[162:165], v151 offset:3072
	s_add_i32 m0, s24, 0xc000
	ds_read_b128 v[166:169], v152
	ds_read_b128 v[170:173], v152 offset:1024
	ds_read_b128 v[174:177], v152 offset:2048
	ds_read_b128 v[178:181], v152 offset:3072
	ds_read_b128 v[182:185], v152 offset:4096
	ds_read_b128 v[186:189], v152 offset:5120
	ds_read_b128 v[190:193], v152 offset:6144
	ds_read_b128 v[194:197], v152 offset:7168
	global_load_lds_dwordx4 v136, s[16:17]
	s_add_i32 m0, s24, 0xe000
	s_nop 0
	global_load_lds_dwordx4 v138, s[16:17]
	s_waitcnt lgkmcnt(8)
	s_barrier
	s_waitcnt lgkmcnt(0)
	v_mfma_f32_16x16x32_f16 v[124:127], v[144:147], v[166:169], v[124:127]
	v_mfma_f32_16x16x32_f16 v[120:123], v[158:161], v[166:169], v[120:123]
	v_mfma_f32_16x16x32_f16 v[108:111], v[144:147], v[174:177], v[108:111]
	v_mfma_f32_16x16x32_f16 v[104:107], v[158:161], v[174:177], v[104:107]
	v_mfma_f32_16x16x32_f16 v[92:95], v[144:147], v[182:185], v[92:95]
	v_mfma_f32_16x16x32_f16 v[88:91], v[158:161], v[182:185], v[88:91]
	v_mfma_f32_16x16x32_f16 v[76:79], v[144:147], v[190:193], v[76:79]
	v_mfma_f32_16x16x32_f16 v[72:75], v[158:161], v[190:193], v[72:75]
	v_mfma_f32_16x16x32_f16 v[124:127], v[154:157], v[170:173], v[124:127]
	v_mfma_f32_16x16x32_f16 v[120:123], v[162:165], v[170:173], v[120:123]
	v_mfma_f32_16x16x32_f16 v[108:111], v[154:157], v[178:181], v[108:111]
	v_mfma_f32_16x16x32_f16 v[104:107], v[162:165], v[178:181], v[104:107]
	v_mfma_f32_16x16x32_f16 v[92:95], v[154:157], v[186:189], v[92:95]
	v_mfma_f32_16x16x32_f16 v[88:91], v[162:165], v[186:189], v[88:91]
	v_mfma_f32_16x16x32_f16 v[76:79], v[154:157], v[194:197], v[76:79]
	v_mfma_f32_16x16x32_f16 v[72:75], v[162:165], v[194:197], v[72:75]
	s_barrier
	s_add_u32 s18, s16, 0xfff80080
	s_addc_u32 s19, s17, -1
	s_cmp_eq_u32 s78, 28
	s_cselect_b32 s21, s5, s19
	s_cselect_b32 s20, s9, s18
	s_cselect_b32 s19, s7, s77
	s_cselect_b32 s18, s15, s76
	s_add_i32 s79, s68, s23
	s_add_u32 s72, s18, s0
	s_addc_u32 s73, s19, s1
	s_mov_b32 m0, s79
	ds_read_b128 v[198:201], v153
	ds_read_b128 v[202:205], v153 offset:1024
	ds_read_b128 v[206:209], v153 offset:2048
	ds_read_b128 v[210:213], v153 offset:3072
	global_load_lds_dwordx4 v130, s[18:19]
	s_add_i32 m0, s79, 0x2000
	s_nop 0
	global_load_lds_dwordx4 v134, s[18:19]
	s_barrier
	s_waitcnt lgkmcnt(0)
	v_mfma_f32_16x16x32_f16 v[116:119], v[198:201], v[166:169], v[116:119]
	v_mfma_f32_16x16x32_f16 v[112:115], v[206:209], v[166:169], v[112:115]
	v_mfma_f32_16x16x32_f16 v[100:103], v[198:201], v[174:177], v[100:103]
	v_mfma_f32_16x16x32_f16 v[96:99], v[206:209], v[174:177], v[96:99]
	v_mfma_f32_16x16x32_f16 v[84:87], v[198:201], v[182:185], v[84:87]
	v_mfma_f32_16x16x32_f16 v[80:83], v[206:209], v[182:185], v[80:83]
	v_mfma_f32_16x16x32_f16 v[68:71], v[198:201], v[190:193], v[68:71]
	v_mfma_f32_16x16x32_f16 v[64:67], v[206:209], v[190:193], v[64:67]
	v_mfma_f32_16x16x32_f16 v[116:119], v[202:205], v[170:173], v[116:119]
	v_mfma_f32_16x16x32_f16 v[112:115], v[210:213], v[170:173], v[112:115]
	v_mfma_f32_16x16x32_f16 v[100:103], v[202:205], v[178:181], v[100:103]
	v_mfma_f32_16x16x32_f16 v[96:99], v[210:213], v[178:181], v[96:99]
	v_mfma_f32_16x16x32_f16 v[84:87], v[202:205], v[186:189], v[84:87]
	v_mfma_f32_16x16x32_f16 v[80:83], v[210:213], v[186:189], v[80:83]
	v_mfma_f32_16x16x32_f16 v[68:71], v[202:205], v[194:197], v[68:71]
	v_mfma_f32_16x16x32_f16 v[64:67], v[210:213], v[194:197], v[64:67]
	s_barrier
	s_mov_b32 m0, s24
	s_add_u32 s74, s20, s0
	s_addc_u32 s75, s21, s1
	ds_read_b128 v[166:169], v152 offset:16384
	ds_read_b128 v[170:173], v152 offset:17408
	ds_read_b128 v[174:177], v152 offset:18432
	ds_read_b128 v[178:181], v152 offset:19456
	ds_read_b128 v[182:185], v152 offset:20480
	ds_read_b128 v[186:189], v152 offset:21504
	ds_read_b128 v[190:193], v152 offset:22528
	ds_read_b128 v[194:197], v152 offset:23552
	global_load_lds_dwordx4 v128, s[20:21]
	s_mov_b32 m0, s25
	s_nop 0
	global_load_lds_dwordx4 v132, s[20:21]
	s_barrier
	s_waitcnt lgkmcnt(0)
	v_mfma_f32_16x16x32_f16 v[60:63], v[144:147], v[166:169], v[60:63]
	v_mfma_f32_16x16x32_f16 v[56:59], v[158:161], v[166:169], v[56:59]
	v_mfma_f32_16x16x32_f16 v[44:47], v[144:147], v[174:177], v[44:47]
	v_mfma_f32_16x16x32_f16 v[40:43], v[158:161], v[174:177], v[40:43]
	v_mfma_f32_16x16x32_f16 v[28:31], v[144:147], v[182:185], v[28:31]
	v_mfma_f32_16x16x32_f16 v[24:27], v[158:161], v[182:185], v[24:27]
	v_mfma_f32_16x16x32_f16 v[12:15], v[144:147], v[190:193], v[12:15]
	v_mfma_f32_16x16x32_f16 v[8:11], v[158:161], v[190:193], v[8:11]
	v_mfma_f32_16x16x32_f16 v[60:63], v[154:157], v[170:173], v[60:63]
	v_mfma_f32_16x16x32_f16 v[56:59], v[162:165], v[170:173], v[56:59]
	v_mfma_f32_16x16x32_f16 v[44:47], v[154:157], v[178:181], v[44:47]
	v_mfma_f32_16x16x32_f16 v[40:43], v[162:165], v[178:181], v[40:43]
	v_mfma_f32_16x16x32_f16 v[28:31], v[154:157], v[186:189], v[28:31]
	v_mfma_f32_16x16x32_f16 v[24:27], v[162:165], v[186:189], v[24:27]
	v_mfma_f32_16x16x32_f16 v[12:15], v[154:157], v[194:197], v[12:15]
	v_mfma_f32_16x16x32_f16 v[8:11], v[162:165], v[194:197], v[8:11]
	s_barrier
	s_add_u32 s80, s18, 0x80000
	s_addc_u32 s81, s19, 0
	s_add_i32 s79, s69, s23
	s_mov_b32 m0, s79
	s_nop 0
	global_load_lds_dwordx4 v130, s[80:81]
	s_add_i32 m0, s79, 0x2000
	s_nop 0
	global_load_lds_dwordx4 v134, s[80:81]
	s_waitcnt vmcnt(6)
	s_barrier
	v_mfma_f32_16x16x32_f16 v[52:55], v[198:201], v[166:169], v[52:55]
	v_mfma_f32_16x16x32_f16 v[48:51], v[206:209], v[166:169], v[48:51]
	v_mfma_f32_16x16x32_f16 v[36:39], v[198:201], v[174:177], v[36:39]
	v_mfma_f32_16x16x32_f16 v[32:35], v[206:209], v[174:177], v[32:35]
	v_mfma_f32_16x16x32_f16 v[20:23], v[198:201], v[182:185], v[20:23]
	v_mfma_f32_16x16x32_f16 v[16:19], v[206:209], v[182:185], v[16:19]
	v_mfma_f32_16x16x32_f16 v[4:7], v[198:201], v[190:193], v[4:7]
	v_mfma_f32_16x16x32_f16 v[0:3], v[206:209], v[190:193], v[0:3]
	v_mfma_f32_16x16x32_f16 v[52:55], v[202:205], v[170:173], v[52:55]
	v_mfma_f32_16x16x32_f16 v[48:51], v[210:213], v[170:173], v[48:51]
	v_mfma_f32_16x16x32_f16 v[36:39], v[202:205], v[178:181], v[36:39]
	v_mfma_f32_16x16x32_f16 v[32:35], v[210:213], v[178:181], v[32:35]
	v_mfma_f32_16x16x32_f16 v[20:23], v[202:205], v[186:189], v[20:23]
	v_mfma_f32_16x16x32_f16 v[16:19], v[210:213], v[186:189], v[16:19]
	v_mfma_f32_16x16x32_f16 v[4:7], v[202:205], v[194:197], v[4:7]
	v_mfma_f32_16x16x32_f16 v[0:3], v[210:213], v[194:197], v[0:3]
	s_barrier
	s_add_i32 s79, 0, 0x18000
	v_add_u32_e32 v162, s79, v149
	ds_read_b128 v[144:147], v162
	ds_read_b128 v[154:157], v162 offset:1024
	ds_read_b128 v[158:161], v162 offset:2048
	ds_read_b128 v[162:165], v162 offset:3072
	s_add_u32 s20, s20, 0x80000
	s_addc_u32 s21, s21, 0
	s_mov_b32 m0, s26
	ds_read_b128 v[166:169], v152 offset:32768
	ds_read_b128 v[170:173], v152 offset:33792
	ds_read_b128 v[174:177], v152 offset:34816
	ds_read_b128 v[178:181], v152 offset:35840
	ds_read_b128 v[182:185], v152 offset:36864
	ds_read_b128 v[186:189], v152 offset:37888
	ds_read_b128 v[190:193], v152 offset:38912
	ds_read_b128 v[194:197], v152 offset:39936
	global_load_lds_dwordx4 v128, s[20:21]
	s_mov_b32 m0, s27
	s_nop 0
	global_load_lds_dwordx4 v132, s[20:21]
	s_waitcnt lgkmcnt(8)
	s_barrier
	s_waitcnt lgkmcnt(0)
	v_mfma_f32_16x16x32_f16 v[124:127], v[144:147], v[166:169], v[124:127]
	v_mfma_f32_16x16x32_f16 v[120:123], v[158:161], v[166:169], v[120:123]
	v_mfma_f32_16x16x32_f16 v[108:111], v[144:147], v[174:177], v[108:111]
	v_mfma_f32_16x16x32_f16 v[104:107], v[158:161], v[174:177], v[104:107]
	v_mfma_f32_16x16x32_f16 v[92:95], v[144:147], v[182:185], v[92:95]
	v_mfma_f32_16x16x32_f16 v[88:91], v[158:161], v[182:185], v[88:91]
	v_mfma_f32_16x16x32_f16 v[76:79], v[144:147], v[190:193], v[76:79]
	v_mfma_f32_16x16x32_f16 v[72:75], v[158:161], v[190:193], v[72:75]
	v_mfma_f32_16x16x32_f16 v[124:127], v[154:157], v[170:173], v[124:127]
	v_mfma_f32_16x16x32_f16 v[120:123], v[162:165], v[170:173], v[120:123]
	v_mfma_f32_16x16x32_f16 v[108:111], v[154:157], v[178:181], v[108:111]
	v_mfma_f32_16x16x32_f16 v[104:107], v[162:165], v[178:181], v[104:107]
	v_mfma_f32_16x16x32_f16 v[92:95], v[154:157], v[186:189], v[92:95]
	v_mfma_f32_16x16x32_f16 v[88:91], v[162:165], v[186:189], v[88:91]
	v_mfma_f32_16x16x32_f16 v[76:79], v[154:157], v[194:197], v[76:79]
	v_mfma_f32_16x16x32_f16 v[72:75], v[162:165], v[194:197], v[72:75]
	s_barrier
	s_add_i32 s20, 0, 0x1c000
	s_add_i32 s21, s79, s23
	v_add_u32_e32 v210, s20, v149
	s_mov_b32 m0, s21
	ds_read_b128 v[198:201], v210
	ds_read_b128 v[202:205], v210 offset:1024
	ds_read_b128 v[206:209], v210 offset:2048
	ds_read_b128 v[210:213], v210 offset:3072
	global_load_lds_dwordx4 v130, s[72:73]
	s_add_i32 m0, s21, 0x2000
	s_nop 0
	global_load_lds_dwordx4 v134, s[72:73]
	s_barrier
	s_waitcnt lgkmcnt(0)
	v_mfma_f32_16x16x32_f16 v[116:119], v[198:201], v[166:169], v[116:119]
	v_mfma_f32_16x16x32_f16 v[112:115], v[206:209], v[166:169], v[112:115]
	v_mfma_f32_16x16x32_f16 v[100:103], v[198:201], v[174:177], v[100:103]
	v_mfma_f32_16x16x32_f16 v[96:99], v[206:209], v[174:177], v[96:99]
	v_mfma_f32_16x16x32_f16 v[84:87], v[198:201], v[182:185], v[84:87]
	v_mfma_f32_16x16x32_f16 v[80:83], v[206:209], v[182:185], v[80:83]
	v_mfma_f32_16x16x32_f16 v[68:71], v[198:201], v[190:193], v[68:71]
	v_mfma_f32_16x16x32_f16 v[64:67], v[206:209], v[190:193], v[64:67]
	v_mfma_f32_16x16x32_f16 v[116:119], v[202:205], v[170:173], v[116:119]
	v_mfma_f32_16x16x32_f16 v[112:115], v[210:213], v[170:173], v[112:115]
	v_mfma_f32_16x16x32_f16 v[100:103], v[202:205], v[178:181], v[100:103]
	v_mfma_f32_16x16x32_f16 v[96:99], v[210:213], v[178:181], v[96:99]
	v_mfma_f32_16x16x32_f16 v[84:87], v[202:205], v[186:189], v[84:87]
	v_mfma_f32_16x16x32_f16 v[80:83], v[210:213], v[186:189], v[80:83]
	v_mfma_f32_16x16x32_f16 v[68:71], v[202:205], v[194:197], v[68:71]
	v_mfma_f32_16x16x32_f16 v[64:67], v[210:213], v[194:197], v[64:67]
	s_barrier
	s_mov_b32 m0, s29
	ds_read_b128 v[166:169], v152 offset:49152
	ds_read_b128 v[170:173], v152 offset:50176
	ds_read_b128 v[174:177], v152 offset:51200
	ds_read_b128 v[178:181], v152 offset:52224
	ds_read_b128 v[182:185], v152 offset:53248
	ds_read_b128 v[186:189], v152 offset:54272
	ds_read_b128 v[190:193], v152 offset:55296
	ds_read_b128 v[194:197], v152 offset:56320
	global_load_lds_dwordx4 v128, s[74:75]
	s_mov_b32 m0, s30
	s_nop 0
	global_load_lds_dwordx4 v132, s[74:75]
	s_barrier
	s_waitcnt lgkmcnt(0)
	v_mfma_f32_16x16x32_f16 v[60:63], v[144:147], v[166:169], v[60:63]
	v_mfma_f32_16x16x32_f16 v[56:59], v[158:161], v[166:169], v[56:59]
	v_mfma_f32_16x16x32_f16 v[44:47], v[144:147], v[174:177], v[44:47]
	v_mfma_f32_16x16x32_f16 v[40:43], v[158:161], v[174:177], v[40:43]
	v_mfma_f32_16x16x32_f16 v[28:31], v[144:147], v[182:185], v[28:31]
	v_mfma_f32_16x16x32_f16 v[24:27], v[158:161], v[182:185], v[24:27]
	v_mfma_f32_16x16x32_f16 v[12:15], v[144:147], v[190:193], v[12:15]
	v_mfma_f32_16x16x32_f16 v[8:11], v[158:161], v[190:193], v[8:11]
	v_mfma_f32_16x16x32_f16 v[60:63], v[154:157], v[170:173], v[60:63]
	v_mfma_f32_16x16x32_f16 v[56:59], v[162:165], v[170:173], v[56:59]
	v_mfma_f32_16x16x32_f16 v[44:47], v[154:157], v[178:181], v[44:47]
	v_mfma_f32_16x16x32_f16 v[40:43], v[162:165], v[178:181], v[40:43]
	v_mfma_f32_16x16x32_f16 v[28:31], v[154:157], v[186:189], v[28:31]
	v_mfma_f32_16x16x32_f16 v[24:27], v[162:165], v[186:189], v[24:27]
	v_mfma_f32_16x16x32_f16 v[12:15], v[154:157], v[194:197], v[12:15]
	v_mfma_f32_16x16x32_f16 v[8:11], v[162:165], v[194:197], v[8:11]
	s_barrier
	s_add_u32 s18, s18, 0x80080
	s_addc_u32 s19, s19, 0
	s_add_i32 s20, s20, s23
	s_mov_b32 m0, s20
	s_nop 0
	global_load_lds_dwordx4 v130, s[18:19]
	s_add_i32 m0, s20, 0x2000
	s_nop 0
	global_load_lds_dwordx4 v134, s[18:19]
	s_waitcnt vmcnt(6)
	s_barrier
	v_mfma_f32_16x16x32_f16 v[52:55], v[198:201], v[166:169], v[52:55]
	v_mfma_f32_16x16x32_f16 v[48:51], v[206:209], v[166:169], v[48:51]
	v_mfma_f32_16x16x32_f16 v[36:39], v[198:201], v[174:177], v[36:39]
	v_mfma_f32_16x16x32_f16 v[32:35], v[206:209], v[174:177], v[32:35]
	v_mfma_f32_16x16x32_f16 v[20:23], v[198:201], v[182:185], v[20:23]
	v_mfma_f32_16x16x32_f16 v[16:19], v[206:209], v[182:185], v[16:19]
	v_mfma_f32_16x16x32_f16 v[4:7], v[198:201], v[190:193], v[4:7]
	v_mfma_f32_16x16x32_f16 v[0:3], v[206:209], v[190:193], v[0:3]
	v_mfma_f32_16x16x32_f16 v[52:55], v[202:205], v[170:173], v[52:55]
	v_mfma_f32_16x16x32_f16 v[48:51], v[210:213], v[170:173], v[48:51]
	v_mfma_f32_16x16x32_f16 v[36:39], v[202:205], v[178:181], v[36:39]
	v_mfma_f32_16x16x32_f16 v[32:35], v[210:213], v[178:181], v[32:35]
	v_mfma_f32_16x16x32_f16 v[20:23], v[202:205], v[186:189], v[20:23]
	v_mfma_f32_16x16x32_f16 v[16:19], v[210:213], v[186:189], v[16:19]
	v_mfma_f32_16x16x32_f16 v[4:7], v[202:205], v[194:197], v[4:7]
	v_mfma_f32_16x16x32_f16 v[0:3], v[210:213], v[194:197], v[0:3]
	s_barrier
	s_add_i32 s78, s78, 2
	s_add_u32 s16, s16, 0x100
	s_addc_u32 s17, s17, 0
	s_add_u32 s76, s76, 0x100
	s_addc_u32 s77, s77, 0
	s_cmp_gt_u32 s78, 29
	s_cbranch_scc0 .LBB0_197
	s_setprio 0
	v_readlane_b32 s52, v254, 21
	v_readlane_b32 s54, v254, 23
	v_readlane_b32 s55, v254, 24
	v_lshl_add_u32 v154, s14, 8, v148
	v_lshl_or_b32 v144, s4, 8, v150
	v_mov_b64_e32 v[146:147], s[54:55]
	v_mad_i64_i32 v[146:147], s[4:5], v154, s70, v[146:147]
	v_cmp_gt_i32_e32 vcc, s71, v144
	v_ashrrev_i32_e32 v145, 31, v144
	v_readlane_b32 s53, v254, 22
	v_readlane_b32 s56, v254, 25
	v_readlane_b32 s57, v254, 26
	v_readlane_b32 s58, v254, 27
	v_readlane_b32 s59, v254, 28
	v_readlane_b32 s60, v254, 29
	v_readlane_b32 s61, v254, 30
	v_readlane_b32 s62, v254, 31
	v_readlane_b32 s63, v254, 32
	v_readlane_b32 s64, v254, 33
	v_readlane_b32 s65, v254, 34
	v_readlane_b32 s66, v254, 35
	v_readlane_b32 s67, v254, 36
	s_and_saveexec_b64 s[4:5], vcc
	s_cbranch_execz .LBB0_200
	v_cvt_pk_f16_f32 v123, v122, v123
	v_cvt_pk_f16_f32 v122, v120, v121
	v_cvt_pk_f16_f32 v121, v126, v127
	v_cvt_pk_f16_f32 v120, v124, v125
	v_lshl_add_u64 v[124:125], v[144:145], 1, v[146:147]
	global_store_dwordx4 v[124:125], v[120:123], off

.LBB0_647:
	ds_read_b128 v[80:83], v243
	ds_read_b128 v[88:91], v243 offset:1024
	ds_read_b128 v[96:99], v243 offset:2048
	ds_read_b128 v[100:103], v243 offset:3072
	s_add_i32 m0, s15, 0xc000
	ds_read_b128 v[120:123], v244
	ds_read_b128 v[132:135], v244 offset:1024
	ds_read_b128 v[136:139], v244 offset:2048
	ds_read_b128 v[148:151], v244 offset:3072
	ds_read_b128 v[152:155], v244 offset:4096
	ds_read_b128 v[156:159], v244 offset:5120
	ds_read_b128 v[160:163], v244 offset:6144
	ds_read_b128 v[172:175], v244 offset:7168
	global_load_lds_dwordx4 v212, s[16:17]
	s_add_i32 m0, s15, 0xe000
	s_nop 0
	global_load_lds_dwordx4 v214, s[16:17]
	s_waitcnt lgkmcnt(8)
	s_barrier
	s_waitcnt lgkmcnt(0)
	v_mfma_f32_16x16x32_f16 v[168:171], v[80:83], v[120:123], v[168:171]
	v_mfma_f32_16x16x32_f16 v[164:167], v[96:99], v[120:123], v[164:167]
	v_mfma_f32_16x16x32_f16 v[128:131], v[80:83], v[136:139], v[128:131]
	v_mfma_f32_16x16x32_f16 v[124:127], v[96:99], v[136:139], v[124:127]
	v_mfma_f32_16x16x32_f16 v[108:111], v[80:83], v[152:155], v[108:111]
	v_mfma_f32_16x16x32_f16 v[104:107], v[96:99], v[152:155], v[104:107]
	v_mfma_f32_16x16x32_f16 v[76:79], v[80:83], v[160:163], v[76:79]
	v_mfma_f32_16x16x32_f16 v[72:75], v[96:99], v[160:163], v[72:75]
	v_mfma_f32_16x16x32_f16 v[168:171], v[88:91], v[132:135], v[168:171]
	v_mfma_f32_16x16x32_f16 v[164:167], v[100:103], v[132:135], v[164:167]
	v_mfma_f32_16x16x32_f16 v[128:131], v[88:91], v[148:151], v[128:131]
	v_mfma_f32_16x16x32_f16 v[124:127], v[100:103], v[148:151], v[124:127]
	v_mfma_f32_16x16x32_f16 v[108:111], v[88:91], v[156:159], v[108:111]
	v_mfma_f32_16x16x32_f16 v[104:107], v[100:103], v[156:159], v[104:107]
	v_mfma_f32_16x16x32_f16 v[76:79], v[88:91], v[172:175], v[76:79]
	v_mfma_f32_16x16x32_f16 v[72:75], v[100:103], v[172:175], v[72:75]
	s_barrier
	s_add_u32 s18, s16, 0xfff80080
	s_addc_u32 s19, s17, -1
	s_cmp_eq_u32 s80, 28
	s_cselect_b32 s21, s9, s19
	s_cselect_b32 s20, s31, s18
	s_cselect_b32 s19, s7, s79
	s_cselect_b32 s18, s77, s78
	s_add_i32 s81, s71, s24
	s_add_u32 s72, s18, s4
	s_addc_u32 s73, s19, s5
	s_mov_b32 m0, s81
	ds_read_b128 v[176:179], v245
	ds_read_b128 v[180:183], v245 offset:1024
	ds_read_b128 v[184:187], v245 offset:2048
	ds_read_b128 v[188:191], v245 offset:3072
	global_load_lds_dwordx4 v206, s[18:19]
	s_add_i32 m0, s81, 0x2000
	s_nop 0
	global_load_lds_dwordx4 v210, s[18:19]
	s_barrier
	s_waitcnt lgkmcnt(0)
	v_mfma_f32_16x16x32_f16 v[144:147], v[176:179], v[120:123], v[144:147]
	v_mfma_f32_16x16x32_f16 v[116:119], v[176:179], v[136:139], v[116:119]
	v_mfma_f32_16x16x32_f16 v[112:115], v[184:187], v[136:139], v[112:115]
	v_mfma_f32_16x16x32_f16 v[92:95], v[176:179], v[152:155], v[92:95]
	v_mfma_f32_16x16x32_f16 v[84:87], v[184:187], v[152:155], v[84:87]
	v_mfma_f32_16x16x32_f16 v[68:71], v[176:179], v[160:163], v[68:71]
	v_mfma_f32_16x16x32_f16 v[64:67], v[184:187], v[160:163], v[64:67]
	v_mfma_f32_16x16x32_f16 v[144:147], v[180:183], v[132:135], v[144:147]
	v_mfma_f32_16x16x32_f16 v[120:123], v[184:187], v[120:123], v[140:143]
	v_mfma_f32_16x16x32_f16 v[116:119], v[180:183], v[148:151], v[116:119]
	v_mfma_f32_16x16x32_f16 v[112:115], v[188:191], v[148:151], v[112:115]
	v_mfma_f32_16x16x32_f16 v[92:95], v[180:183], v[156:159], v[92:95]
	v_mfma_f32_16x16x32_f16 v[84:87], v[188:191], v[156:159], v[84:87]
	v_mfma_f32_16x16x32_f16 v[68:71], v[180:183], v[172:175], v[68:71]
	v_mfma_f32_16x16x32_f16 v[64:67], v[188:191], v[172:175], v[64:67]
	v_mfma_f32_16x16x32_f16 v[120:123], v[188:191], v[132:135], v[120:123]
	s_barrier
	s_mov_b32 m0, s15
	s_add_u32 s74, s20, s4
	s_addc_u32 s75, s21, s5
	ds_read_b128 v[132:135], v244 offset:16384
	ds_read_b128 v[136:139], v244 offset:17408
	ds_read_b128 v[140:143], v244 offset:18432
	ds_read_b128 v[148:151], v244 offset:19456
	ds_read_b128 v[152:155], v244 offset:20480
	ds_read_b128 v[156:159], v244 offset:21504
	ds_read_b128 v[160:163], v244 offset:22528
	ds_read_b128 v[172:175], v244 offset:23552
	global_load_lds_dwordx4 v204, s[20:21]
	s_mov_b32 m0, s25
	s_nop 0
	global_load_lds_dwordx4 v208, s[20:21]
	s_barrier
	s_waitcnt lgkmcnt(0)
	v_mfma_f32_16x16x32_f16 v[60:63], v[80:83], v[132:135], v[60:63]
	v_mfma_f32_16x16x32_f16 v[56:59], v[96:99], v[132:135], v[56:59]
	v_mfma_f32_16x16x32_f16 v[44:47], v[80:83], v[140:143], v[44:47]
	v_mfma_f32_16x16x32_f16 v[40:43], v[96:99], v[140:143], v[40:43]
	v_mfma_f32_16x16x32_f16 v[28:31], v[80:83], v[152:155], v[28:31]
	v_mfma_f32_16x16x32_f16 v[24:27], v[96:99], v[152:155], v[24:27]
	v_mfma_f32_16x16x32_f16 v[12:15], v[80:83], v[160:163], v[12:15]
	v_mfma_f32_16x16x32_f16 v[8:11], v[96:99], v[160:163], v[8:11]
	v_mfma_f32_16x16x32_f16 v[60:63], v[88:91], v[136:139], v[60:63]
	v_mfma_f32_16x16x32_f16 v[56:59], v[100:103], v[136:139], v[56:59]
	v_mfma_f32_16x16x32_f16 v[44:47], v[88:91], v[148:151], v[44:47]
	v_mfma_f32_16x16x32_f16 v[40:43], v[100:103], v[148:151], v[40:43]
	v_mfma_f32_16x16x32_f16 v[28:31], v[88:91], v[156:159], v[28:31]
	v_mfma_f32_16x16x32_f16 v[24:27], v[100:103], v[156:159], v[24:27]
	v_mfma_f32_16x16x32_f16 v[12:15], v[88:91], v[172:175], v[12:15]
	v_mfma_f32_16x16x32_f16 v[8:11], v[100:103], v[172:175], v[8:11]
	s_barrier
	s_add_u32 s82, s18, 0x80000
	s_addc_u32 s83, s19, 0
	s_add_i32 s81, s76, s24
	s_mov_b32 m0, s81
	s_nop 0
	global_load_lds_dwordx4 v206, s[82:83]
	s_add_i32 m0, s81, 0x2000
	s_nop 0
	global_load_lds_dwordx4 v210, s[82:83]
	s_waitcnt vmcnt(6)
	s_barrier
	v_mfma_f32_16x16x32_f16 v[52:55], v[176:179], v[132:135], v[52:55]
	v_mfma_f32_16x16x32_f16 v[48:51], v[184:187], v[132:135], v[48:51]
	v_mfma_f32_16x16x32_f16 v[36:39], v[176:179], v[140:143], v[36:39]
	v_mfma_f32_16x16x32_f16 v[32:35], v[184:187], v[140:143], v[32:35]
	v_mfma_f32_16x16x32_f16 v[20:23], v[176:179], v[152:155], v[20:23]
	v_mfma_f32_16x16x32_f16 v[16:19], v[184:187], v[152:155], v[16:19]
	v_mfma_f32_16x16x32_f16 v[4:7], v[176:179], v[160:163], v[4:7]
	v_mfma_f32_16x16x32_f16 v[0:3], v[184:187], v[160:163], v[0:3]
	v_mfma_f32_16x16x32_f16 v[52:55], v[180:183], v[136:139], v[52:55]
	v_mfma_f32_16x16x32_f16 v[48:51], v[188:191], v[136:139], v[48:51]
	v_mfma_f32_16x16x32_f16 v[36:39], v[180:183], v[148:151], v[36:39]
	v_mfma_f32_16x16x32_f16 v[32:35], v[188:191], v[148:151], v[32:35]
	v_mfma_f32_16x16x32_f16 v[20:23], v[180:183], v[156:159], v[20:23]
	v_mfma_f32_16x16x32_f16 v[16:19], v[188:191], v[156:159], v[16:19]
	v_mfma_f32_16x16x32_f16 v[4:7], v[180:183], v[172:175], v[4:7]
	v_mfma_f32_16x16x32_f16 v[0:3], v[188:191], v[172:175], v[0:3]
	s_barrier
	s_add_i32 s81, 0, 0x18000
	v_add_u32_e32 v100, s81, v241
	ds_read_b128 v[80:83], v100
	ds_read_b128 v[88:91], v100 offset:1024
	ds_read_b128 v[96:99], v100 offset:2048
	ds_read_b128 v[100:103], v100 offset:3072
	s_add_u32 s20, s20, 0x80000
	s_addc_u32 s21, s21, 0
	s_mov_b32 m0, s26
	ds_read_b128 v[132:135], v244 offset:32768
	ds_read_b128 v[136:139], v244 offset:33792
	ds_read_b128 v[148:151], v244 offset:34816
	ds_read_b128 v[152:155], v244 offset:35840
	ds_read_b128 v[156:159], v244 offset:36864
	ds_read_b128 v[160:163], v244 offset:37888
	ds_read_b128 v[172:175], v244 offset:38912
	ds_read_b128 v[176:179], v244 offset:39936
	global_load_lds_dwordx4 v204, s[20:21]
	s_mov_b32 m0, s27
	s_nop 0
	global_load_lds_dwordx4 v208, s[20:21]
	s_waitcnt lgkmcnt(8)
	s_barrier
	s_waitcnt lgkmcnt(0)
	v_mfma_f32_16x16x32_f16 v[140:143], v[80:83], v[132:135], v[168:171]
	v_mfma_f32_16x16x32_f16 v[168:171], v[88:91], v[136:139], v[140:143]
	v_mfma_f32_16x16x32_f16 v[140:143], v[96:99], v[132:135], v[164:167]
	v_mfma_f32_16x16x32_f16 v[128:131], v[80:83], v[148:151], v[128:131]
	v_mfma_f32_16x16x32_f16 v[124:127], v[96:99], v[148:151], v[124:127]
	v_mfma_f32_16x16x32_f16 v[108:111], v[80:83], v[156:159], v[108:111]
	v_mfma_f32_16x16x32_f16 v[104:107], v[96:99], v[156:159], v[104:107]
	v_mfma_f32_16x16x32_f16 v[76:79], v[80:83], v[172:175], v[76:79]
	v_mfma_f32_16x16x32_f16 v[72:75], v[96:99], v[172:175], v[72:75]
	v_mfma_f32_16x16x32_f16 v[164:167], v[100:103], v[136:139], v[140:143]
	v_mfma_f32_16x16x32_f16 v[128:131], v[88:91], v[152:155], v[128:131]
	v_mfma_f32_16x16x32_f16 v[124:127], v[100:103], v[152:155], v[124:127]
	v_mfma_f32_16x16x32_f16 v[108:111], v[88:91], v[160:163], v[108:111]
	v_mfma_f32_16x16x32_f16 v[104:107], v[100:103], v[160:163], v[104:107]
	v_mfma_f32_16x16x32_f16 v[76:79], v[88:91], v[176:179], v[76:79]
	v_mfma_f32_16x16x32_f16 v[72:75], v[100:103], v[176:179], v[72:75]
	s_barrier
	s_add_i32 s20, 0, 0x1c000
	v_add_u32_e32 v140, s20, v241
	s_add_i32 s21, s81, s24
	ds_read_b128 v[180:183], v140
	ds_read_b128 v[184:187], v140 offset:1024
	ds_read_b128 v[188:191], v140 offset:2048
	ds_read_b128 v[192:195], v140 offset:3072
	s_mov_b32 m0, s21
	s_nop 0
	global_load_lds_dwordx4 v206, s[72:73]
	s_add_i32 m0, s21, 0x2000
	s_nop 0
	global_load_lds_dwordx4 v210, s[72:73]
	s_barrier
	s_waitcnt lgkmcnt(0)
	v_mfma_f32_16x16x32_f16 v[140:143], v[180:183], v[132:135], v[144:147]
	v_mfma_f32_16x16x32_f16 v[120:123], v[188:191], v[132:135], v[120:123]
	v_mfma_f32_16x16x32_f16 v[116:119], v[180:183], v[148:151], v[116:119]
	v_mfma_f32_16x16x32_f16 v[112:115], v[188:191], v[148:151], v[112:115]
	v_mfma_f32_16x16x32_f16 v[92:95], v[180:183], v[156:159], v[92:95]
	v_mfma_f32_16x16x32_f16 v[84:87], v[188:191], v[156:159], v[84:87]
	v_mfma_f32_16x16x32_f16 v[68:71], v[180:183], v[172:175], v[68:71]
	v_mfma_f32_16x16x32_f16 v[64:67], v[188:191], v[172:175], v[64:67]
	v_mfma_f32_16x16x32_f16 v[144:147], v[184:187], v[136:139], v[140:143]
	v_mfma_f32_16x16x32_f16 v[140:143], v[192:195], v[136:139], v[120:123]
	v_mfma_f32_16x16x32_f16 v[116:119], v[184:187], v[152:155], v[116:119]
	v_mfma_f32_16x16x32_f16 v[112:115], v[192:195], v[152:155], v[112:115]
	v_mfma_f32_16x16x32_f16 v[92:95], v[184:187], v[160:163], v[92:95]
	v_mfma_f32_16x16x32_f16 v[84:87], v[192:195], v[160:163], v[84:87]
	v_mfma_f32_16x16x32_f16 v[68:71], v[184:187], v[176:179], v[68:71]
	v_mfma_f32_16x16x32_f16 v[64:67], v[192:195], v[176:179], v[64:67]
	s_barrier
	s_mov_b32 m0, s35
	ds_read_b128 v[120:123], v244 offset:49152
	ds_read_b128 v[132:135], v244 offset:50176
	ds_read_b128 v[136:139], v244 offset:51200
	ds_read_b128 v[148:151], v244 offset:52224
	ds_read_b128 v[152:155], v244 offset:53248
	ds_read_b128 v[156:159], v244 offset:54272
	ds_read_b128 v[160:163], v244 offset:55296
	ds_read_b128 v[172:175], v244 offset:56320
	global_load_lds_dwordx4 v204, s[74:75]
	s_mov_b32 m0, s68
	s_nop 0
	global_load_lds_dwordx4 v208, s[74:75]
	s_barrier
	s_waitcnt lgkmcnt(0)
	v_mfma_f32_16x16x32_f16 v[60:63], v[80:83], v[120:123], v[60:63]
	v_mfma_f32_16x16x32_f16 v[56:59], v[96:99], v[120:123], v[56:59]
	v_mfma_f32_16x16x32_f16 v[44:47], v[80:83], v[136:139], v[44:47]
	v_mfma_f32_16x16x32_f16 v[40:43], v[96:99], v[136:139], v[40:43]
	v_mfma_f32_16x16x32_f16 v[28:31], v[80:83], v[152:155], v[28:31]
	v_mfma_f32_16x16x32_f16 v[24:27], v[96:99], v[152:155], v[24:27]
	v_mfma_f32_16x16x32_f16 v[12:15], v[80:83], v[160:163], v[12:15]
	v_mfma_f32_16x16x32_f16 v[8:11], v[96:99], v[160:163], v[8:11]
	v_mfma_f32_16x16x32_f16 v[60:63], v[88:91], v[132:135], v[60:63]
	v_mfma_f32_16x16x32_f16 v[56:59], v[100:103], v[132:135], v[56:59]
	v_mfma_f32_16x16x32_f16 v[44:47], v[88:91], v[148:151], v[44:47]
	v_mfma_f32_16x16x32_f16 v[40:43], v[100:103], v[148:151], v[40:43]
	v_mfma_f32_16x16x32_f16 v[28:31], v[88:91], v[156:159], v[28:31]
	v_mfma_f32_16x16x32_f16 v[24:27], v[100:103], v[156:159], v[24:27]
	v_mfma_f32_16x16x32_f16 v[12:15], v[88:91], v[172:175], v[12:15]
	v_mfma_f32_16x16x32_f16 v[8:11], v[100:103], v[172:175], v[8:11]
	s_barrier
	s_add_u32 s18, s18, 0x80080
	s_addc_u32 s19, s19, 0
	s_add_i32 s20, s20, s24
	s_mov_b32 m0, s20
	s_nop 0
	global_load_lds_dwordx4 v206, s[18:19]
	s_add_i32 m0, s20, 0x2000
	s_nop 0
	global_load_lds_dwordx4 v210, s[18:19]
	s_waitcnt vmcnt(6)
	s_barrier
	v_mfma_f32_16x16x32_f16 v[52:55], v[180:183], v[120:123], v[52:55]
	v_mfma_f32_16x16x32_f16 v[48:51], v[188:191], v[120:123], v[48:51]
	v_mfma_f32_16x16x32_f16 v[36:39], v[180:183], v[136:139], v[36:39]
	v_mfma_f32_16x16x32_f16 v[32:35], v[188:191], v[136:139], v[32:35]
	v_mfma_f32_16x16x32_f16 v[20:23], v[180:183], v[152:155], v[20:23]
	v_mfma_f32_16x16x32_f16 v[16:19], v[188:191], v[152:155], v[16:19]
	v_mfma_f32_16x16x32_f16 v[4:7], v[180:183], v[160:163], v[4:7]
	v_mfma_f32_16x16x32_f16 v[0:3], v[188:191], v[160:163], v[0:3]
	v_mfma_f32_16x16x32_f16 v[52:55], v[184:187], v[132:135], v[52:55]
	v_mfma_f32_16x16x32_f16 v[48:51], v[192:195], v[132:135], v[48:51]
	v_mfma_f32_16x16x32_f16 v[36:39], v[184:187], v[148:151], v[36:39]
	v_mfma_f32_16x16x32_f16 v[32:35], v[192:195], v[148:151], v[32:35]
	v_mfma_f32_16x16x32_f16 v[20:23], v[184:187], v[156:159], v[20:23]
	v_mfma_f32_16x16x32_f16 v[16:19], v[192:195], v[156:159], v[16:19]
	v_mfma_f32_16x16x32_f16 v[4:7], v[184:187], v[172:175], v[4:7]
	v_mfma_f32_16x16x32_f16 v[0:3], v[192:195], v[172:175], v[0:3]
	s_barrier
	s_add_i32 s80, s80, 2
	s_add_u32 s16, s16, 0x100
	s_addc_u32 s17, s17, 0
	s_add_u32 s78, s78, 0x100
	s_addc_u32 s79, s79, 0
	s_cmp_gt_u32 s80, 29
	s_cbranch_scc0 .LBB0_647
	s_setprio 0
	s_lshl_b32 s7, s14, 8
	s_add_i32 s9, s7, 0xffffe000
	s_lshr_b32 s9, s9, 11
	s_mulk_i32 s9, 0x1800
	s_addk_i32 s9, 0x1800
	s_cmp_gt_i32 s14, 31
	s_cselect_b32 s16, s9, 0
	s_ashr_i32 s17, s16, 31
	v_lshl_or_b32 v120, s30, 8, v242
	s_lshl_b64 s[16:17], s[16:17], 2
	s_add_u32 s16, s29, s16
	v_ashrrev_i32_e32 v121, 31, v120
	v_add_u32_e32 v122, s7, v240
	s_addc_u32 s17, s34, s17
	v_lshlrev_b64 v[220:221], 1, v[120:121]
	v_ashrrev_i32_e32 v123, 31, v122
	v_lshl_add_u64 v[88:89], v[120:121], 2, s[16:17]
	v_lshl_add_u64 v[120:121], s[40:41], 0, v[220:221]
	v_lshlrev_b64 v[236:237], 12, v[122:123]
	v_lshl_add_u64 v[132:133], v[120:121], 0, v[236:237]
	global_load_dwordx4 v[96:99], v[88:89], off offset:16
	global_load_dwordx4 v[100:103], v[88:89], off
	global_load_dwordx4 v[80:83], v[88:89], off offset:528
	s_nop 0
	global_load_dwordx4 v[88:91], v[88:89], off offset:512
	s_nop 0
	global_load_dwordx4 v[246:249], v[132:133], off nt
	global_load_dwordx4 v[200:203], v[132:133], off offset:256 nt
	v_or_b32_e32 v132, 16, v122
	v_ashrrev_i32_e32 v133, 31, v132
	v_lshlrev_b64 v[234:235], 12, v[132:133]
	v_lshl_add_u64 v[132:133], v[120:121], 0, v[234:235]
	global_load_dwordx4 v[196:199], v[132:133], off nt
	global_load_dwordx4 v[192:195], v[132:133], off offset:256 nt
	v_or_b32_e32 v132, 32, v122
	v_ashrrev_i32_e32 v133, 31, v132
	v_lshlrev_b64 v[232:233], 12, v[132:133]
	v_lshl_add_u64 v[132:133], v[120:121], 0, v[232:233]
	global_load_dwordx4 v[188:191], v[132:133], off nt
	global_load_dwordx4 v[184:187], v[132:133], off offset:256 nt
	v_or_b32_e32 v122, 48, v122
	v_ashrrev_i32_e32 v123, 31, v122
	v_lshlrev_b64 v[230:231], 12, v[122:123]
	v_lshl_add_u64 v[122:123], v[120:121], 0, v[230:231]
	global_load_dwordx4 v[180:183], v[122:123], off nt
	global_load_dwordx4 v[176:179], v[122:123], off offset:256 nt
	s_mov_b64 s[16:17], 0x80000
	v_lshl_add_u64 v[228:229], v[236:237], 0, s[16:17]
	v_lshl_add_u64 v[122:123], v[120:121], 0, v[228:229]
	global_load_dwordx4 v[172:175], v[122:123], off nt
	global_load_dwordx4 v[160:163], v[122:123], off offset:256 nt
	s_mov_b64 s[16:17], 0x90000
	v_lshl_add_u64 v[226:227], v[236:237], 0, s[16:17]
	v_lshl_add_u64 v[122:123], v[120:121], 0, v[226:227]
	global_load_dwordx4 v[156:159], v[122:123], off nt
	global_load_dwordx4 v[152:155], v[122:123], off offset:256 nt
	s_mov_b64 s[16:17], 0xa0000
	v_lshl_add_u64 v[224:225], v[236:237], 0, s[16:17]
	v_lshl_add_u64 v[122:123], v[120:121], 0, v[224:225]
	global_load_dwordx4 v[148:151], v[122:123], off nt
	global_load_dwordx4 v[136:139], v[122:123], off offset:256 nt
	s_mov_b64 s[16:17], 0xb0000
	v_lshl_add_u64 v[222:223], v[236:237], 0, s[16:17]
	v_lshl_add_u64 v[120:121], v[120:121], 0, v[222:223]
	global_load_dwordx4 v[132:135], v[120:121], off nt
	s_nop 0
	global_load_dwordx4 v[120:123], v[120:121], off offset:256 nt
	s_and_b64 vcc, exec, s[2:3]
	s_mov_b32 s30, s6
	s_mov_b32 s14, s8
	s_mov_b64 s[18:19], s[12:13]
	s_mov_b64 s[16:17], s[10:11]
	s_waitcnt vmcnt(0)
	v_cvt_f32_f16_e32 v250, v246
	v_cvt_f32_f16_sdwa v251, v246 dst_sel:DWORD dst_unused:UNUSED_PAD src0_sel:WORD_1
	v_pk_fma_f32 v[168:169], v[168:169], v[100:101], v[250:251]
	s_nop 0
	v_cvt_pk_f16_f32 v246, v168, v169
	v_cvt_f32_f16_e32 v168, v248
	v_cvt_f32_f16_sdwa v169, v248 dst_sel:DWORD dst_unused:UNUSED_PAD src0_sel:WORD_1
	v_pk_fma_f32 v[164:165], v[164:165], v[96:97], v[168:169]
	s_nop 0
	v_cvt_pk_f16_f32 v248, v164, v165
	v_cvt_f32_f16_e32 v164, v247
	v_cvt_f32_f16_sdwa v165, v247 dst_sel:DWORD dst_unused:UNUSED_PAD src0_sel:WORD_1
	v_pk_fma_f32 v[164:165], v[170:171], v[102:103], v[164:165]
	s_nop 0
	v_cvt_pk_f16_f32 v247, v164, v165
	v_cvt_f32_f16_e32 v164, v249
	v_cvt_f32_f16_sdwa v165, v249 dst_sel:DWORD dst_unused:UNUSED_PAD src0_sel:WORD_1
	v_pk_fma_f32 v[164:165], v[166:167], v[98:99], v[164:165]
	s_nop 0
	v_cvt_pk_f16_f32 v249, v164, v165
	v_lshl_add_u64 v[164:165], s[0:1], 0, v[236:237]
	v_lshl_add_u64 v[168:169], v[164:165], 0, v[220:221]
	v_cvt_f32_f16_e32 v164, v200
	v_cvt_f32_f16_sdwa v165, v200 dst_sel:DWORD dst_unused:UNUSED_PAD src0_sel:WORD_1
	global_store_dwordx4 v[168:169], v[246:249], off
	v_pk_fma_f32 v[144:145], v[144:145], v[88:89], v[164:165]
	s_nop 0
	v_cvt_pk_f16_f32 v164, v144, v145
	v_cvt_f32_f16_e32 v144, v202
	v_cvt_f32_f16_sdwa v145, v202 dst_sel:DWORD dst_unused:UNUSED_PAD src0_sel:WORD_1
	v_pk_fma_f32 v[140:141], v[140:141], v[80:81], v[144:145]
	s_nop 0
	v_cvt_pk_f16_f32 v166, v140, v141
	v_cvt_f32_f16_e32 v140, v201
	v_cvt_f32_f16_sdwa v141, v201 dst_sel:DWORD dst_unused:UNUSED_PAD src0_sel:WORD_1
	v_pk_fma_f32 v[140:141], v[146:147], v[90:91], v[140:141]
	s_nop 0
	v_cvt_pk_f16_f32 v165, v140, v141
	v_cvt_f32_f16_e32 v140, v203
	v_cvt_f32_f16_sdwa v141, v203 dst_sel:DWORD dst_unused:UNUSED_PAD src0_sel:WORD_1
	v_pk_fma_f32 v[140:141], v[142:143], v[82:83], v[140:141]
	s_nop 0
	v_cvt_pk_f16_f32 v167, v140, v141
	v_cvt_f32_f16_e32 v140, v196
	v_cvt_f32_f16_sdwa v141, v196 dst_sel:DWORD dst_unused:UNUSED_PAD src0_sel:WORD_1
	global_store_dwordx4 v[168:169], v[164:167], off offset:256
	v_pk_fma_f32 v[128:129], v[128:129], v[100:101], v[140:141]
	s_nop 0
	v_cvt_pk_f16_f32 v140, v128, v129
	v_cvt_f32_f16_e32 v128, v198
	v_cvt_f32_f16_sdwa v129, v198 dst_sel:DWORD dst_unused:UNUSED_PAD src0_sel:WORD_1
	v_pk_fma_f32 v[124:125], v[124:125], v[96:97], v[128:129]
	s_nop 0
	v_cvt_pk_f16_f32 v142, v124, v125
	v_cvt_f32_f16_e32 v124, v197
	v_cvt_f32_f16_sdwa v125, v197 dst_sel:DWORD dst_unused:UNUSED_PAD src0_sel:WORD_1
	v_pk_fma_f32 v[124:125], v[130:131], v[102:103], v[124:125]
	s_nop 0
	v_cvt_pk_f16_f32 v141, v124, v125
	v_cvt_f32_f16_e32 v124, v199
	v_cvt_f32_f16_sdwa v125, v199 dst_sel:DWORD dst_unused:UNUSED_PAD src0_sel:WORD_1
	v_pk_fma_f32 v[124:125], v[126:127], v[98:99], v[124:125]
	s_nop 0
	v_cvt_pk_f16_f32 v143, v124, v125
	v_lshl_add_u64 v[124:125], s[0:1], 0, v[234:235]
	v_lshl_add_u64 v[128:129], v[124:125], 0, v[220:221]
	v_cvt_f32_f16_e32 v124, v192
	v_cvt_f32_f16_sdwa v125, v192 dst_sel:DWORD dst_unused:UNUSED_PAD src0_sel:WORD_1
	global_store_dwordx4 v[128:129], v[140:143], off
	v_pk_fma_f32 v[116:117], v[116:117], v[88:89], v[124:125]
	s_nop 0
	v_cvt_pk_f16_f32 v124, v116, v117
	v_cvt_f32_f16_e32 v116, v194
	v_cvt_f32_f16_sdwa v117, v194 dst_sel:DWORD dst_unused:UNUSED_PAD src0_sel:WORD_1
	v_pk_fma_f32 v[112:113], v[112:113], v[80:81], v[116:117]
	s_nop 0
	v_cvt_pk_f16_f32 v126, v112, v113
	v_cvt_f32_f16_e32 v112, v193
	v_cvt_f32_f16_sdwa v113, v193 dst_sel:DWORD dst_unused:UNUSED_PAD src0_sel:WORD_1
	v_pk_fma_f32 v[112:113], v[118:119], v[90:91], v[112:113]
	s_nop 0
	v_cvt_pk_f16_f32 v125, v112, v113
	v_cvt_f32_f16_e32 v112, v195
	v_cvt_f32_f16_sdwa v113, v195 dst_sel:DWORD dst_unused:UNUSED_PAD src0_sel:WORD_1
	v_pk_fma_f32 v[112:113], v[114:115], v[82:83], v[112:113]
	s_nop 0
	v_cvt_pk_f16_f32 v127, v112, v113
	v_cvt_f32_f16_e32 v112, v188
	v_cvt_f32_f16_sdwa v113, v188 dst_sel:DWORD dst_unused:UNUSED_PAD src0_sel:WORD_1
	global_store_dwordx4 v[128:129], v[124:127], off offset:256
	v_pk_fma_f32 v[108:109], v[108:109], v[100:101], v[112:113]
	s_nop 0
	v_cvt_pk_f16_f32 v112, v108, v109
	v_cvt_f32_f16_e32 v108, v190
	v_cvt_f32_f16_sdwa v109, v190 dst_sel:DWORD dst_unused:UNUSED_PAD src0_sel:WORD_1
	v_pk_fma_f32 v[104:105], v[104:105], v[96:97], v[108:109]
	s_nop 0
	v_cvt_pk_f16_f32 v114, v104, v105
	v_cvt_f32_f16_e32 v104, v189
	v_cvt_f32_f16_sdwa v105, v189 dst_sel:DWORD dst_unused:UNUSED_PAD src0_sel:WORD_1
	v_pk_fma_f32 v[104:105], v[110:111], v[102:103], v[104:105]
	s_nop 0
	v_cvt_pk_f16_f32 v113, v104, v105
	v_cvt_f32_f16_e32 v104, v191
	v_cvt_f32_f16_sdwa v105, v191 dst_sel:DWORD dst_unused:UNUSED_PAD src0_sel:WORD_1
	v_pk_fma_f32 v[104:105], v[106:107], v[98:99], v[104:105]
	s_nop 0
	v_cvt_pk_f16_f32 v115, v104, v105
	v_lshl_add_u64 v[104:105], s[0:1], 0, v[232:233]
	v_lshl_add_u64 v[108:109], v[104:105], 0, v[220:221]
	v_cvt_f32_f16_e32 v104, v184
	v_cvt_f32_f16_sdwa v105, v184 dst_sel:DWORD dst_unused:UNUSED_PAD src0_sel:WORD_1
	global_store_dwordx4 v[108:109], v[112:115], off
	v_pk_fma_f32 v[92:93], v[92:93], v[88:89], v[104:105]
	s_nop 0
	v_cvt_pk_f16_f32 v104, v92, v93
	v_cvt_f32_f16_e32 v92, v186
	v_cvt_f32_f16_sdwa v93, v186 dst_sel:DWORD dst_unused:UNUSED_PAD src0_sel:WORD_1
	v_pk_fma_f32 v[84:85], v[84:85], v[80:81], v[92:93]
	s_nop 0
	v_cvt_pk_f16_f32 v106, v84, v85
	v_cvt_f32_f16_e32 v84, v185
	v_cvt_f32_f16_sdwa v85, v185 dst_sel:DWORD dst_unused:UNUSED_PAD src0_sel:WORD_1
	v_pk_fma_f32 v[84:85], v[94:95], v[90:91], v[84:85]
	s_nop 0
	v_cvt_pk_f16_f32 v105, v84, v85
	v_cvt_f32_f16_e32 v84, v187
	v_cvt_f32_f16_sdwa v85, v187 dst_sel:DWORD dst_unused:UNUSED_PAD src0_sel:WORD_1
	v_pk_fma_f32 v[84:85], v[86:87], v[82:83], v[84:85]
	s_nop 0
	v_cvt_pk_f16_f32 v107, v84, v85
	v_cvt_f32_f16_e32 v84, v180
	v_cvt_f32_f16_sdwa v85, v180 dst_sel:DWORD dst_unused:UNUSED_PAD src0_sel:WORD_1
	global_store_dwordx4 v[108:109], v[104:107], off offset:256
	v_pk_fma_f32 v[76:77], v[76:77], v[100:101], v[84:85]
	s_nop 0
	v_cvt_pk_f16_f32 v84, v76, v77
	v_cvt_f32_f16_e32 v76, v182
	v_cvt_f32_f16_sdwa v77, v182 dst_sel:DWORD dst_unused:UNUSED_PAD src0_sel:WORD_1
	v_pk_fma_f32 v[72:73], v[72:73], v[96:97], v[76:77]
	s_nop 0
	v_cvt_pk_f16_f32 v86, v72, v73
	v_cvt_f32_f16_e32 v72, v181
	v_cvt_f32_f16_sdwa v73, v181 dst_sel:DWORD dst_unused:UNUSED_PAD src0_sel:WORD_1
	v_pk_fma_f32 v[72:73], v[78:79], v[102:103], v[72:73]
	s_nop 0
	v_cvt_pk_f16_f32 v85, v72, v73
	v_cvt_f32_f16_e32 v72, v183
	v_cvt_f32_f16_sdwa v73, v183 dst_sel:DWORD dst_unused:UNUSED_PAD src0_sel:WORD_1
	v_pk_fma_f32 v[72:73], v[74:75], v[98:99], v[72:73]
	s_nop 0
	v_cvt_pk_f16_f32 v87, v72, v73
	v_lshl_add_u64 v[72:73], s[0:1], 0, v[230:231]
	v_lshl_add_u64 v[76:77], v[72:73], 0, v[220:221]
	v_cvt_f32_f16_e32 v72, v176
	v_cvt_f32_f16_sdwa v73, v176 dst_sel:DWORD dst_unused:UNUSED_PAD src0_sel:WORD_1
	global_store_dwordx4 v[76:77], v[84:87], off
	v_pk_fma_f32 v[68:69], v[68:69], v[88:89], v[72:73]
	s_nop 0
	v_cvt_pk_f16_f32 v72, v68, v69
	v_cvt_f32_f16_e32 v68, v178
	v_cvt_f32_f16_sdwa v69, v178 dst_sel:DWORD dst_unused:UNUSED_PAD src0_sel:WORD_1
	v_pk_fma_f32 v[64:65], v[64:65], v[80:81], v[68:69]
	s_nop 0
	v_cvt_pk_f16_f32 v74, v64, v65
	v_cvt_f32_f16_e32 v64, v177
	v_cvt_f32_f16_sdwa v65, v177 dst_sel:DWORD dst_unused:UNUSED_PAD src0_sel:WORD_1
	v_pk_fma_f32 v[64:65], v[70:71], v[90:91], v[64:65]
	s_nop 0
	v_cvt_pk_f16_f32 v73, v64, v65
	v_cvt_f32_f16_e32 v64, v179
	v_cvt_f32_f16_sdwa v65, v179 dst_sel:DWORD dst_unused:UNUSED_PAD src0_sel:WORD_1
	v_pk_fma_f32 v[64:65], v[66:67], v[82:83], v[64:65]
	s_nop 0
	v_cvt_pk_f16_f32 v75, v64, v65
	v_cvt_f32_f16_e32 v64, v172
	v_cvt_f32_f16_sdwa v65, v172 dst_sel:DWORD dst_unused:UNUSED_PAD src0_sel:WORD_1
	global_store_dwordx4 v[76:77], v[72:75], off offset:256
	v_pk_fma_f32 v[60:61], v[60:61], v[100:101], v[64:65]
	s_nop 0
	v_cvt_pk_f16_f32 v64, v60, v61
	v_cvt_f32_f16_e32 v60, v174
	v_cvt_f32_f16_sdwa v61, v174 dst_sel:DWORD dst_unused:UNUSED_PAD src0_sel:WORD_1
	v_pk_fma_f32 v[56:57], v[56:57], v[96:97], v[60:61]
	s_nop 0
	v_cvt_pk_f16_f32 v66, v56, v57
	v_cvt_f32_f16_e32 v56, v173
	v_cvt_f32_f16_sdwa v57, v173 dst_sel:DWORD dst_unused:UNUSED_PAD src0_sel:WORD_1
	v_pk_fma_f32 v[56:57], v[62:63], v[102:103], v[56:57]
	s_nop 0
	v_cvt_pk_f16_f32 v65, v56, v57
	v_cvt_f32_f16_e32 v56, v175
	v_cvt_f32_f16_sdwa v57, v175 dst_sel:DWORD dst_unused:UNUSED_PAD src0_sel:WORD_1
	v_pk_fma_f32 v[56:57], v[58:59], v[98:99], v[56:57]
	s_nop 0
	v_cvt_pk_f16_f32 v67, v56, v57
	v_lshl_add_u64 v[56:57], s[0:1], 0, v[228:229]
	v_lshl_add_u64 v[60:61], v[56:57], 0, v[220:221]
	v_cvt_f32_f16_e32 v56, v160
	v_cvt_f32_f16_sdwa v57, v160 dst_sel:DWORD dst_unused:UNUSED_PAD src0_sel:WORD_1
	global_store_dwordx4 v[60:61], v[64:67], off
	v_pk_fma_f32 v[52:53], v[52:53], v[88:89], v[56:57]
	s_nop 0
	v_cvt_pk_f16_f32 v56, v52, v53
	v_cvt_f32_f16_e32 v52, v162
	v_cvt_f32_f16_sdwa v53, v162 dst_sel:DWORD dst_unused:UNUSED_PAD src0_sel:WORD_1
	v_pk_fma_f32 v[48:49], v[48:49], v[80:81], v[52:53]
	s_nop 0
	v_cvt_pk_f16_f32 v58, v48, v49
	v_cvt_f32_f16_e32 v48, v161
	v_cvt_f32_f16_sdwa v49, v161 dst_sel:DWORD dst_unused:UNUSED_PAD src0_sel:WORD_1
	v_pk_fma_f32 v[48:49], v[54:55], v[90:91], v[48:49]
	s_nop 0
	v_cvt_pk_f16_f32 v57, v48, v49
	v_cvt_f32_f16_e32 v48, v163
	v_cvt_f32_f16_sdwa v49, v163 dst_sel:DWORD dst_unused:UNUSED_PAD src0_sel:WORD_1
	v_pk_fma_f32 v[48:49], v[50:51], v[82:83], v[48:49]
	s_nop 0
	v_cvt_pk_f16_f32 v59, v48, v49
	v_cvt_f32_f16_e32 v48, v156
	v_cvt_f32_f16_sdwa v49, v156 dst_sel:DWORD dst_unused:UNUSED_PAD src0_sel:WORD_1
	global_store_dwordx4 v[60:61], v[56:59], off offset:256
	v_pk_fma_f32 v[44:45], v[44:45], v[100:101], v[48:49]
	s_nop 0
	v_cvt_pk_f16_f32 v48, v44, v45
	v_cvt_f32_f16_e32 v44, v158
	v_cvt_f32_f16_sdwa v45, v158 dst_sel:DWORD dst_unused:UNUSED_PAD src0_sel:WORD_1
	v_pk_fma_f32 v[40:41], v[40:41], v[96:97], v[44:45]
	s_nop 0
	v_cvt_pk_f16_f32 v50, v40, v41
	v_cvt_f32_f16_e32 v40, v157
	v_cvt_f32_f16_sdwa v41, v157 dst_sel:DWORD dst_unused:UNUSED_PAD src0_sel:WORD_1
	v_pk_fma_f32 v[40:41], v[46:47], v[102:103], v[40:41]
	s_nop 0
	v_cvt_pk_f16_f32 v49, v40, v41
	v_cvt_f32_f16_e32 v40, v159
	v_cvt_f32_f16_sdwa v41, v159 dst_sel:DWORD dst_unused:UNUSED_PAD src0_sel:WORD_1
	v_pk_fma_f32 v[40:41], v[42:43], v[98:99], v[40:41]
	s_nop 0
	v_cvt_pk_f16_f32 v51, v40, v41
	v_lshl_add_u64 v[40:41], s[0:1], 0, v[226:227]
	v_lshl_add_u64 v[44:45], v[40:41], 0, v[220:221]
	v_cvt_f32_f16_e32 v40, v152
	v_cvt_f32_f16_sdwa v41, v152 dst_sel:DWORD dst_unused:UNUSED_PAD src0_sel:WORD_1
	global_store_dwordx4 v[44:45], v[48:51], off
	v_pk_fma_f32 v[36:37], v[36:37], v[88:89], v[40:41]
	s_nop 0
	v_cvt_pk_f16_f32 v40, v36, v37
	v_cvt_f32_f16_e32 v36, v154
	v_cvt_f32_f16_sdwa v37, v154 dst_sel:DWORD dst_unused:UNUSED_PAD src0_sel:WORD_1
	v_pk_fma_f32 v[32:33], v[32:33], v[80:81], v[36:37]
	s_nop 0
	v_cvt_pk_f16_f32 v42, v32, v33
	v_cvt_f32_f16_e32 v32, v153
	v_cvt_f32_f16_sdwa v33, v153 dst_sel:DWORD dst_unused:UNUSED_PAD src0_sel:WORD_1
	v_pk_fma_f32 v[32:33], v[38:39], v[90:91], v[32:33]
	s_nop 0
	v_cvt_pk_f16_f32 v41, v32, v33
	v_cvt_f32_f16_e32 v32, v155
	v_cvt_f32_f16_sdwa v33, v155 dst_sel:DWORD dst_unused:UNUSED_PAD src0_sel:WORD_1
	v_pk_fma_f32 v[32:33], v[34:35], v[82:83], v[32:33]
	s_nop 0
	v_cvt_pk_f16_f32 v43, v32, v33
	v_cvt_f32_f16_e32 v32, v148
	v_cvt_f32_f16_sdwa v33, v148 dst_sel:DWORD dst_unused:UNUSED_PAD src0_sel:WORD_1
	global_store_dwordx4 v[44:45], v[40:43], off offset:256
	v_pk_fma_f32 v[28:29], v[28:29], v[100:101], v[32:33]
	s_nop 0
	v_cvt_pk_f16_f32 v32, v28, v29
	v_cvt_f32_f16_e32 v28, v150
	v_cvt_f32_f16_sdwa v29, v150 dst_sel:DWORD dst_unused:UNUSED_PAD src0_sel:WORD_1
	v_pk_fma_f32 v[24:25], v[24:25], v[96:97], v[28:29]
	s_nop 0
	v_cvt_pk_f16_f32 v34, v24, v25
	v_cvt_f32_f16_e32 v24, v149
	v_cvt_f32_f16_sdwa v25, v149 dst_sel:DWORD dst_unused:UNUSED_PAD src0_sel:WORD_1
	v_pk_fma_f32 v[24:25], v[30:31], v[102:103], v[24:25]
	s_nop 0
	v_cvt_pk_f16_f32 v33, v24, v25
	v_cvt_f32_f16_e32 v24, v151
	v_cvt_f32_f16_sdwa v25, v151 dst_sel:DWORD dst_unused:UNUSED_PAD src0_sel:WORD_1
	v_pk_fma_f32 v[24:25], v[26:27], v[98:99], v[24:25]
	s_nop 0
	v_cvt_pk_f16_f32 v35, v24, v25
	v_lshl_add_u64 v[24:25], s[0:1], 0, v[224:225]
	v_lshl_add_u64 v[28:29], v[24:25], 0, v[220:221]
	v_cvt_f32_f16_e32 v24, v136
	v_cvt_f32_f16_sdwa v25, v136 dst_sel:DWORD dst_unused:UNUSED_PAD src0_sel:WORD_1
	global_store_dwordx4 v[28:29], v[32:35], off
	v_pk_fma_f32 v[20:21], v[20:21], v[88:89], v[24:25]
	s_nop 0
	v_cvt_pk_f16_f32 v24, v20, v21
	v_cvt_f32_f16_e32 v20, v138
	v_cvt_f32_f16_sdwa v21, v138 dst_sel:DWORD dst_unused:UNUSED_PAD src0_sel:WORD_1
	v_pk_fma_f32 v[16:17], v[16:17], v[80:81], v[20:21]
	s_nop 0
	v_cvt_pk_f16_f32 v26, v16, v17
	v_cvt_f32_f16_e32 v16, v137
	v_cvt_f32_f16_sdwa v17, v137 dst_sel:DWORD dst_unused:UNUSED_PAD src0_sel:WORD_1
	v_pk_fma_f32 v[16:17], v[22:23], v[90:91], v[16:17]
	s_nop 0
	v_cvt_pk_f16_f32 v25, v16, v17
	v_cvt_f32_f16_e32 v16, v139
	v_cvt_f32_f16_sdwa v17, v139 dst_sel:DWORD dst_unused:UNUSED_PAD src0_sel:WORD_1
	v_pk_fma_f32 v[16:17], v[18:19], v[82:83], v[16:17]
	s_nop 0
	v_cvt_pk_f16_f32 v27, v16, v17
	v_cvt_f32_f16_e32 v16, v132
	v_cvt_f32_f16_sdwa v17, v132 dst_sel:DWORD dst_unused:UNUSED_PAD src0_sel:WORD_1
	global_store_dwordx4 v[28:29], v[24:27], off offset:256
	v_pk_fma_f32 v[12:13], v[12:13], v[100:101], v[16:17]
	s_nop 0
	v_cvt_pk_f16_f32 v16, v12, v13
	v_cvt_f32_f16_e32 v12, v134
	v_cvt_f32_f16_sdwa v13, v134 dst_sel:DWORD dst_unused:UNUSED_PAD src0_sel:WORD_1
	v_pk_fma_f32 v[8:9], v[8:9], v[96:97], v[12:13]
	s_nop 0
	v_cvt_pk_f16_f32 v18, v8, v9
	v_cvt_f32_f16_e32 v8, v133
	v_cvt_f32_f16_sdwa v9, v133 dst_sel:DWORD dst_unused:UNUSED_PAD src0_sel:WORD_1
	v_pk_fma_f32 v[8:9], v[14:15], v[102:103], v[8:9]
	s_nop 0
	v_cvt_pk_f16_f32 v17, v8, v9
	v_cvt_f32_f16_e32 v8, v135
	v_cvt_f32_f16_sdwa v9, v135 dst_sel:DWORD dst_unused:UNUSED_PAD src0_sel:WORD_1
	v_pk_fma_f32 v[8:9], v[10:11], v[98:99], v[8:9]
	s_nop 0
	v_cvt_pk_f16_f32 v19, v8, v9
	v_lshl_add_u64 v[8:9], s[0:1], 0, v[222:223]
	v_lshl_add_u64 v[12:13], v[8:9], 0, v[220:221]
	v_cvt_f32_f16_e32 v8, v120
	v_cvt_f32_f16_sdwa v9, v120 dst_sel:DWORD dst_unused:UNUSED_PAD src0_sel:WORD_1
	global_store_dwordx4 v[12:13], v[16:19], off
	v_pk_fma_f32 v[4:5], v[4:5], v[88:89], v[8:9]
	s_nop 0
	v_cvt_pk_f16_f32 v8, v4, v5
	v_cvt_f32_f16_e32 v4, v122
	v_cvt_f32_f16_sdwa v5, v122 dst_sel:DWORD dst_unused:UNUSED_PAD src0_sel:WORD_1
	v_pk_fma_f32 v[0:1], v[0:1], v[80:81], v[4:5]
	s_nop 0
	v_cvt_pk_f16_f32 v10, v0, v1
	v_cvt_f32_f16_e32 v0, v121
	v_cvt_f32_f16_sdwa v1, v121 dst_sel:DWORD dst_unused:UNUSED_PAD src0_sel:WORD_1
	v_pk_fma_f32 v[0:1], v[6:7], v[90:91], v[0:1]
	s_nop 0
	v_cvt_pk_f16_f32 v9, v0, v1
	v_cvt_f32_f16_e32 v0, v123
	v_cvt_f32_f16_sdwa v1, v123 dst_sel:DWORD dst_unused:UNUSED_PAD src0_sel:WORD_1
	v_pk_fma_f32 v[0:1], v[2:3], v[82:83], v[0:1]
	s_nop 0
	v_cvt_pk_f16_f32 v11, v0, v1
	global_store_dwordx4 v[12:13], v[8:11], off offset:256
	s_cbranch_vccz .LBB0_640
	s_waitcnt vmcnt(0)
	s_cmpk_gt_u32 s22, 0xff
	s_cbranch_scc1 .LBB0_651
	s_barrier

.LBB0_1185:
	ds_read_b128 v[88:91], v243
	ds_read_b128 v[96:99], v243 offset:1024
	ds_read_b128 v[108:111], v243 offset:2048
	ds_read_b128 v[116:119], v243 offset:3072
	s_add_i32 m0, s23, 0xc000
	ds_read_b128 v[128:131], v244
	ds_read_b128 v[136:139], v244 offset:1024
	ds_read_b128 v[144:147], v244 offset:2048
	ds_read_b128 v[148:151], v244 offset:3072
	ds_read_b128 v[152:155], v244 offset:4096
	ds_read_b128 v[164:167], v244 offset:5120
	ds_read_b128 v[168:171], v244 offset:6144
	ds_read_b128 v[172:175], v244 offset:7168
	global_load_lds_dwordx4 v212, s[24:25]
	s_add_i32 m0, s23, 0xe000
	s_nop 0
	global_load_lds_dwordx4 v214, s[24:25]
	s_waitcnt lgkmcnt(8)
	s_barrier
	s_waitcnt lgkmcnt(0)
	v_mfma_f32_16x16x32_f16 v[160:163], v[88:91], v[128:131], v[160:163]
	v_mfma_f32_16x16x32_f16 v[156:159], v[108:111], v[128:131], v[156:159]
	v_mfma_f32_16x16x32_f16 v[124:127], v[88:91], v[144:147], v[124:127]
	v_mfma_f32_16x16x32_f16 v[120:123], v[108:111], v[144:147], v[120:123]
	v_mfma_f32_16x16x32_f16 v[100:103], v[88:91], v[152:155], v[100:103]
	v_mfma_f32_16x16x32_f16 v[92:95], v[108:111], v[152:155], v[92:95]
	v_mfma_f32_16x16x32_f16 v[76:79], v[88:91], v[168:171], v[76:79]
	v_mfma_f32_16x16x32_f16 v[72:75], v[108:111], v[168:171], v[72:75]
	v_mfma_f32_16x16x32_f16 v[160:163], v[96:99], v[136:139], v[160:163]
	v_mfma_f32_16x16x32_f16 v[156:159], v[116:119], v[136:139], v[156:159]
	v_mfma_f32_16x16x32_f16 v[124:127], v[96:99], v[148:151], v[124:127]
	v_mfma_f32_16x16x32_f16 v[120:123], v[116:119], v[148:151], v[120:123]
	v_mfma_f32_16x16x32_f16 v[100:103], v[96:99], v[164:167], v[100:103]
	v_mfma_f32_16x16x32_f16 v[92:95], v[116:119], v[164:167], v[92:95]
	v_mfma_f32_16x16x32_f16 v[76:79], v[96:99], v[172:175], v[76:79]
	v_mfma_f32_16x16x32_f16 v[72:75], v[116:119], v[172:175], v[72:75]
	s_barrier
	s_add_u32 s26, s24, 0xfff80080
	s_addc_u32 s27, s25, -1
	s_cmp_eq_u32 s64, 28
	s_cselect_b32 s29, s17, s27
	s_cselect_b32 s28, s31, s26
	s_cselect_b32 s27, s15, s63
	s_cselect_b32 s26, s61, s62
	s_add_i32 s65, s59, s44
	s_add_u32 s72, s26, s6
	s_addc_u32 s73, s27, s7
	s_mov_b32 m0, s65
	ds_read_b128 v[176:179], v245
	ds_read_b128 v[180:183], v245 offset:1024
	ds_read_b128 v[184:187], v245 offset:2048
	ds_read_b128 v[188:191], v245 offset:3072
	global_load_lds_dwordx4 v206, s[26:27]
	s_add_i32 m0, s65, 0x2000
	s_nop 0
	global_load_lds_dwordx4 v210, s[26:27]
	s_barrier
	s_waitcnt lgkmcnt(0)
	v_mfma_f32_16x16x32_f16 v[140:143], v[176:179], v[128:131], v[140:143]
	v_mfma_f32_16x16x32_f16 v[112:115], v[176:179], v[144:147], v[112:115]
	v_mfma_f32_16x16x32_f16 v[104:107], v[184:187], v[144:147], v[104:107]
	v_mfma_f32_16x16x32_f16 v[84:87], v[176:179], v[152:155], v[84:87]
	v_mfma_f32_16x16x32_f16 v[80:83], v[184:187], v[152:155], v[80:83]
	v_mfma_f32_16x16x32_f16 v[68:71], v[176:179], v[168:171], v[68:71]
	v_mfma_f32_16x16x32_f16 v[64:67], v[184:187], v[168:171], v[64:67]
	v_mfma_f32_16x16x32_f16 v[140:143], v[180:183], v[136:139], v[140:143]
	v_mfma_f32_16x16x32_f16 v[128:131], v[184:187], v[128:131], v[132:135]
	v_mfma_f32_16x16x32_f16 v[112:115], v[180:183], v[148:151], v[112:115]
	v_mfma_f32_16x16x32_f16 v[104:107], v[188:191], v[148:151], v[104:107]
	v_mfma_f32_16x16x32_f16 v[84:87], v[180:183], v[164:167], v[84:87]
	v_mfma_f32_16x16x32_f16 v[80:83], v[188:191], v[164:167], v[80:83]
	v_mfma_f32_16x16x32_f16 v[68:71], v[180:183], v[172:175], v[68:71]
	v_mfma_f32_16x16x32_f16 v[64:67], v[188:191], v[172:175], v[64:67]
	v_mfma_f32_16x16x32_f16 v[128:131], v[188:191], v[136:139], v[128:131]
	s_barrier
	s_mov_b32 m0, s23
	s_add_u32 s74, s28, s6
	s_addc_u32 s75, s29, s7
	ds_read_b128 v[132:135], v244 offset:16384
	ds_read_b128 v[136:139], v244 offset:17408
	ds_read_b128 v[144:147], v244 offset:18432
	ds_read_b128 v[148:151], v244 offset:19456
	ds_read_b128 v[152:155], v244 offset:20480
	ds_read_b128 v[164:167], v244 offset:21504
	ds_read_b128 v[168:171], v244 offset:22528
	ds_read_b128 v[172:175], v244 offset:23552
	global_load_lds_dwordx4 v204, s[28:29]
	s_mov_b32 m0, s45
	s_nop 0
	global_load_lds_dwordx4 v208, s[28:29]
	s_barrier
	s_waitcnt lgkmcnt(0)
	v_mfma_f32_16x16x32_f16 v[60:63], v[88:91], v[132:135], v[60:63]
	v_mfma_f32_16x16x32_f16 v[56:59], v[108:111], v[132:135], v[56:59]
	v_mfma_f32_16x16x32_f16 v[44:47], v[88:91], v[144:147], v[44:47]
	v_mfma_f32_16x16x32_f16 v[40:43], v[108:111], v[144:147], v[40:43]
	v_mfma_f32_16x16x32_f16 v[28:31], v[88:91], v[152:155], v[28:31]
	v_mfma_f32_16x16x32_f16 v[24:27], v[108:111], v[152:155], v[24:27]
	v_mfma_f32_16x16x32_f16 v[12:15], v[88:91], v[168:171], v[12:15]
	v_mfma_f32_16x16x32_f16 v[8:11], v[108:111], v[168:171], v[8:11]
	v_mfma_f32_16x16x32_f16 v[60:63], v[96:99], v[136:139], v[60:63]
	v_mfma_f32_16x16x32_f16 v[56:59], v[116:119], v[136:139], v[56:59]
	v_mfma_f32_16x16x32_f16 v[44:47], v[96:99], v[148:151], v[44:47]
	v_mfma_f32_16x16x32_f16 v[40:43], v[116:119], v[148:151], v[40:43]
	v_mfma_f32_16x16x32_f16 v[28:31], v[96:99], v[164:167], v[28:31]
	v_mfma_f32_16x16x32_f16 v[24:27], v[116:119], v[164:167], v[24:27]
	v_mfma_f32_16x16x32_f16 v[12:15], v[96:99], v[172:175], v[12:15]
	v_mfma_f32_16x16x32_f16 v[8:11], v[116:119], v[172:175], v[8:11]
	s_barrier
	s_add_u32 s66, s26, 0x80000
	s_addc_u32 s67, s27, 0
	s_add_i32 s65, s60, s44
	s_mov_b32 m0, s65
	s_nop 0
	global_load_lds_dwordx4 v206, s[66:67]
	s_add_i32 m0, s65, 0x2000
	s_nop 0
	global_load_lds_dwordx4 v210, s[66:67]
	s_waitcnt vmcnt(6)
	s_barrier
	v_mfma_f32_16x16x32_f16 v[52:55], v[176:179], v[132:135], v[52:55]
	v_mfma_f32_16x16x32_f16 v[48:51], v[184:187], v[132:135], v[48:51]
	v_mfma_f32_16x16x32_f16 v[36:39], v[176:179], v[144:147], v[36:39]
	v_mfma_f32_16x16x32_f16 v[32:35], v[184:187], v[144:147], v[32:35]
	v_mfma_f32_16x16x32_f16 v[20:23], v[176:179], v[152:155], v[20:23]
	v_mfma_f32_16x16x32_f16 v[16:19], v[184:187], v[152:155], v[16:19]
	v_mfma_f32_16x16x32_f16 v[4:7], v[176:179], v[168:171], v[4:7]
	v_mfma_f32_16x16x32_f16 v[0:3], v[184:187], v[168:171], v[0:3]
	v_mfma_f32_16x16x32_f16 v[52:55], v[180:183], v[136:139], v[52:55]
	v_mfma_f32_16x16x32_f16 v[48:51], v[188:191], v[136:139], v[48:51]
	v_mfma_f32_16x16x32_f16 v[36:39], v[180:183], v[148:151], v[36:39]
	v_mfma_f32_16x16x32_f16 v[32:35], v[188:191], v[148:151], v[32:35]
	v_mfma_f32_16x16x32_f16 v[20:23], v[180:183], v[164:167], v[20:23]
	v_mfma_f32_16x16x32_f16 v[16:19], v[188:191], v[164:167], v[16:19]
	v_mfma_f32_16x16x32_f16 v[4:7], v[180:183], v[172:175], v[4:7]
	v_mfma_f32_16x16x32_f16 v[0:3], v[188:191], v[172:175], v[0:3]
	s_barrier
	s_add_i32 s65, 0, 0x18000
	v_add_u32_e32 v116, s65, v241
	ds_read_b128 v[88:91], v116
	ds_read_b128 v[96:99], v116 offset:1024
	ds_read_b128 v[108:111], v116 offset:2048
	ds_read_b128 v[116:119], v116 offset:3072
	s_add_u32 s28, s28, 0x80000
	s_addc_u32 s29, s29, 0
	s_mov_b32 m0, s48
	ds_read_b128 v[132:135], v244 offset:32768
	ds_read_b128 v[136:139], v244 offset:33792
	ds_read_b128 v[144:147], v244 offset:34816
	ds_read_b128 v[148:151], v244 offset:35840
	ds_read_b128 v[152:155], v244 offset:36864
	ds_read_b128 v[164:167], v244 offset:37888
	ds_read_b128 v[168:171], v244 offset:38912
	ds_read_b128 v[172:175], v244 offset:39936
	global_load_lds_dwordx4 v204, s[28:29]
	s_mov_b32 m0, s49
	s_nop 0
	global_load_lds_dwordx4 v208, s[28:29]
	s_waitcnt lgkmcnt(8)
	s_barrier
	s_waitcnt lgkmcnt(0)
	v_mfma_f32_16x16x32_f16 v[160:163], v[88:91], v[132:135], v[160:163]
	v_mfma_f32_16x16x32_f16 v[156:159], v[108:111], v[132:135], v[156:159]
	v_mfma_f32_16x16x32_f16 v[124:127], v[88:91], v[144:147], v[124:127]
	v_mfma_f32_16x16x32_f16 v[120:123], v[108:111], v[144:147], v[120:123]
	v_mfma_f32_16x16x32_f16 v[100:103], v[88:91], v[152:155], v[100:103]
	v_mfma_f32_16x16x32_f16 v[92:95], v[108:111], v[152:155], v[92:95]
	v_mfma_f32_16x16x32_f16 v[76:79], v[88:91], v[168:171], v[76:79]
	v_mfma_f32_16x16x32_f16 v[72:75], v[108:111], v[168:171], v[72:75]
	v_mfma_f32_16x16x32_f16 v[160:163], v[96:99], v[136:139], v[160:163]
	v_mfma_f32_16x16x32_f16 v[156:159], v[116:119], v[136:139], v[156:159]
	v_mfma_f32_16x16x32_f16 v[124:127], v[96:99], v[148:151], v[124:127]
	v_mfma_f32_16x16x32_f16 v[120:123], v[116:119], v[148:151], v[120:123]
	v_mfma_f32_16x16x32_f16 v[100:103], v[96:99], v[164:167], v[100:103]
	v_mfma_f32_16x16x32_f16 v[92:95], v[116:119], v[164:167], v[92:95]
	v_mfma_f32_16x16x32_f16 v[76:79], v[96:99], v[172:175], v[76:79]
	v_mfma_f32_16x16x32_f16 v[72:75], v[116:119], v[172:175], v[72:75]
	s_barrier
	s_add_i32 s28, 0, 0x1c000
	s_add_i32 s29, s65, s44
	v_add_u32_e32 v188, s28, v241
	s_mov_b32 m0, s29
	ds_read_b128 v[176:179], v188
	ds_read_b128 v[180:183], v188 offset:1024
	ds_read_b128 v[184:187], v188 offset:2048
	ds_read_b128 v[188:191], v188 offset:3072
	global_load_lds_dwordx4 v206, s[72:73]
	s_add_i32 m0, s29, 0x2000
	s_nop 0
	global_load_lds_dwordx4 v210, s[72:73]
	s_barrier
	s_waitcnt lgkmcnt(0)
	v_mfma_f32_16x16x32_f16 v[140:143], v[176:179], v[132:135], v[140:143]
	v_mfma_f32_16x16x32_f16 v[128:131], v[184:187], v[132:135], v[128:131]
	v_mfma_f32_16x16x32_f16 v[112:115], v[176:179], v[144:147], v[112:115]
	v_mfma_f32_16x16x32_f16 v[104:107], v[184:187], v[144:147], v[104:107]
	v_mfma_f32_16x16x32_f16 v[84:87], v[176:179], v[152:155], v[84:87]
	v_mfma_f32_16x16x32_f16 v[80:83], v[184:187], v[152:155], v[80:83]
	v_mfma_f32_16x16x32_f16 v[68:71], v[176:179], v[168:171], v[68:71]
	v_mfma_f32_16x16x32_f16 v[64:67], v[184:187], v[168:171], v[64:67]
	v_mfma_f32_16x16x32_f16 v[140:143], v[180:183], v[136:139], v[140:143]
	v_mfma_f32_16x16x32_f16 v[132:135], v[188:191], v[136:139], v[128:131]
	v_mfma_f32_16x16x32_f16 v[112:115], v[180:183], v[148:151], v[112:115]
	v_mfma_f32_16x16x32_f16 v[104:107], v[188:191], v[148:151], v[104:107]
	v_mfma_f32_16x16x32_f16 v[84:87], v[180:183], v[164:167], v[84:87]
	v_mfma_f32_16x16x32_f16 v[80:83], v[188:191], v[164:167], v[80:83]
	v_mfma_f32_16x16x32_f16 v[68:71], v[180:183], v[172:175], v[68:71]
	v_mfma_f32_16x16x32_f16 v[64:67], v[188:191], v[172:175], v[64:67]
	s_barrier
	s_mov_b32 m0, s51
	ds_read_b128 v[128:131], v244 offset:49152
	ds_read_b128 v[136:139], v244 offset:50176
	ds_read_b128 v[144:147], v244 offset:51200
	ds_read_b128 v[148:151], v244 offset:52224
	ds_read_b128 v[152:155], v244 offset:53248
	ds_read_b128 v[164:167], v244 offset:54272
	ds_read_b128 v[168:171], v244 offset:55296
	ds_read_b128 v[172:175], v244 offset:56320
	global_load_lds_dwordx4 v204, s[74:75]
	s_mov_b32 m0, s54
	s_nop 0
	global_load_lds_dwordx4 v208, s[74:75]
	s_barrier
	s_waitcnt lgkmcnt(0)
	v_mfma_f32_16x16x32_f16 v[60:63], v[88:91], v[128:131], v[60:63]
	v_mfma_f32_16x16x32_f16 v[56:59], v[108:111], v[128:131], v[56:59]
	v_mfma_f32_16x16x32_f16 v[44:47], v[88:91], v[144:147], v[44:47]
	v_mfma_f32_16x16x32_f16 v[40:43], v[108:111], v[144:147], v[40:43]
	v_mfma_f32_16x16x32_f16 v[28:31], v[88:91], v[152:155], v[28:31]
	v_mfma_f32_16x16x32_f16 v[24:27], v[108:111], v[152:155], v[24:27]
	v_mfma_f32_16x16x32_f16 v[12:15], v[88:91], v[168:171], v[12:15]
	v_mfma_f32_16x16x32_f16 v[8:11], v[108:111], v[168:171], v[8:11]
	v_mfma_f32_16x16x32_f16 v[60:63], v[96:99], v[136:139], v[60:63]
	v_mfma_f32_16x16x32_f16 v[56:59], v[116:119], v[136:139], v[56:59]
	v_mfma_f32_16x16x32_f16 v[44:47], v[96:99], v[148:151], v[44:47]
	v_mfma_f32_16x16x32_f16 v[40:43], v[116:119], v[148:151], v[40:43]
	v_mfma_f32_16x16x32_f16 v[28:31], v[96:99], v[164:167], v[28:31]
	v_mfma_f32_16x16x32_f16 v[24:27], v[116:119], v[164:167], v[24:27]
	v_mfma_f32_16x16x32_f16 v[12:15], v[96:99], v[172:175], v[12:15]
	v_mfma_f32_16x16x32_f16 v[8:11], v[116:119], v[172:175], v[8:11]
	s_barrier
	s_add_u32 s26, s26, 0x80080
	s_addc_u32 s27, s27, 0
	s_add_i32 s28, s28, s44
	s_mov_b32 m0, s28
	s_nop 0
	global_load_lds_dwordx4 v206, s[26:27]
	s_add_i32 m0, s28, 0x2000
	s_nop 0
	global_load_lds_dwordx4 v210, s[26:27]
	s_waitcnt vmcnt(6)
	s_barrier
	v_mfma_f32_16x16x32_f16 v[52:55], v[176:179], v[128:131], v[52:55]
	v_mfma_f32_16x16x32_f16 v[48:51], v[184:187], v[128:131], v[48:51]
	v_mfma_f32_16x16x32_f16 v[36:39], v[176:179], v[144:147], v[36:39]
	v_mfma_f32_16x16x32_f16 v[32:35], v[184:187], v[144:147], v[32:35]
	v_mfma_f32_16x16x32_f16 v[20:23], v[176:179], v[152:155], v[20:23]
	v_mfma_f32_16x16x32_f16 v[16:19], v[184:187], v[152:155], v[16:19]
	v_mfma_f32_16x16x32_f16 v[4:7], v[176:179], v[168:171], v[4:7]
	v_mfma_f32_16x16x32_f16 v[0:3], v[184:187], v[168:171], v[0:3]
	v_mfma_f32_16x16x32_f16 v[52:55], v[180:183], v[136:139], v[52:55]
	v_mfma_f32_16x16x32_f16 v[48:51], v[188:191], v[136:139], v[48:51]
	v_mfma_f32_16x16x32_f16 v[36:39], v[180:183], v[148:151], v[36:39]
	v_mfma_f32_16x16x32_f16 v[32:35], v[188:191], v[148:151], v[32:35]
	v_mfma_f32_16x16x32_f16 v[20:23], v[180:183], v[164:167], v[20:23]
	v_mfma_f32_16x16x32_f16 v[16:19], v[188:191], v[164:167], v[16:19]
	v_mfma_f32_16x16x32_f16 v[4:7], v[180:183], v[172:175], v[4:7]
	v_mfma_f32_16x16x32_f16 v[0:3], v[188:191], v[172:175], v[0:3]
	s_barrier
	s_add_i32 s64, s64, 2
	s_add_u32 s24, s24, 0x100
	s_addc_u32 s25, s25, 0
	s_add_u32 s62, s62, 0x100
	s_addc_u32 s63, s63, 0
	s_cmp_gt_u32 s64, 29
	s_cbranch_scc0 .LBB0_1185
	s_setprio 0
	s_lshl_b32 s15, s22, 8
	s_add_i32 s17, s15, 0xffffe000
	s_lshr_b32 s17, s17, 11
	s_mulk_i32 s17, 0x1800
	s_addk_i32 s17, 0x1800
	s_cmp_gt_i32 s22, 31
	s_cselect_b32 s24, s17, 0
	s_ashr_i32 s25, s24, 31
	v_lshl_or_b32 v128, s30, 8, v242
	s_lshl_b64 s[24:25], s[24:25], 2
	s_add_u32 s24, s42, s24
	v_ashrrev_i32_e32 v129, 31, v128
	v_add_u32_e32 v130, s15, v240
	s_addc_u32 s25, s43, s25
	v_lshlrev_b64 v[220:221], 1, v[128:129]
	v_ashrrev_i32_e32 v131, 31, v130
	v_lshl_add_u64 v[96:97], v[128:129], 2, s[24:25]
	v_lshl_add_u64 v[128:129], s[4:5], 0, v[220:221]
	v_lshlrev_b64 v[236:237], 12, v[130:131]
	v_lshl_add_u64 v[136:137], v[128:129], 0, v[236:237]
	global_load_dwordx4 v[108:111], v[96:97], off offset:16
	global_load_dwordx4 v[116:119], v[96:97], off
	global_load_dwordx4 v[88:91], v[96:97], off offset:528
	s_nop 0
	global_load_dwordx4 v[96:99], v[96:97], off offset:512
	s_nop 0
	global_load_dwordx4 v[246:249], v[136:137], off nt
	global_load_dwordx4 v[200:203], v[136:137], off offset:256 nt
	v_or_b32_e32 v136, 16, v130
	v_ashrrev_i32_e32 v137, 31, v136
	v_lshlrev_b64 v[234:235], 12, v[136:137]
	v_lshl_add_u64 v[136:137], v[128:129], 0, v[234:235]
	global_load_dwordx4 v[196:199], v[136:137], off nt
	global_load_dwordx4 v[192:195], v[136:137], off offset:256 nt
	v_or_b32_e32 v136, 32, v130
	v_ashrrev_i32_e32 v137, 31, v136
	v_lshlrev_b64 v[232:233], 12, v[136:137]
	v_lshl_add_u64 v[136:137], v[128:129], 0, v[232:233]
	global_load_dwordx4 v[188:191], v[136:137], off nt
	global_load_dwordx4 v[184:187], v[136:137], off offset:256 nt
	v_readlane_b32 s64, v254, 21
	v_readlane_b32 s68, v254, 25
	v_readlane_b32 s69, v254, 26
	s_mov_b64 s[56:57], s[68:69]
	v_or_b32_e32 v130, 48, v130
	v_ashrrev_i32_e32 v131, 31, v130
	v_lshlrev_b64 v[230:231], 12, v[130:131]
	v_lshl_add_u64 v[130:131], v[128:129], 0, v[230:231]
	global_load_dwordx4 v[180:183], v[130:131], off nt
	global_load_dwordx4 v[176:179], v[130:131], off offset:256 nt
	v_lshl_add_u64 v[228:229], v[236:237], 0, s[0:1]
	v_lshl_add_u64 v[130:131], v[128:129], 0, v[228:229]
	global_load_dwordx4 v[172:175], v[130:131], off nt
	global_load_dwordx4 v[168:171], v[130:131], off offset:256 nt
	v_lshl_add_u64 v[226:227], v[236:237], 0, s[8:9]
	v_lshl_add_u64 v[130:131], v[128:129], 0, v[226:227]
	global_load_dwordx4 v[164:167], v[130:131], off nt
	global_load_dwordx4 v[152:155], v[130:131], off offset:256 nt
	v_lshl_add_u64 v[224:225], v[236:237], 0, s[10:11]
	v_lshl_add_u64 v[130:131], v[128:129], 0, v[224:225]
	global_load_dwordx4 v[148:151], v[130:131], off nt
	global_load_dwordx4 v[144:147], v[130:131], off offset:256 nt
	v_lshl_add_u64 v[222:223], v[236:237], 0, s[12:13]
	v_lshl_add_u64 v[128:129], v[128:129], 0, v[222:223]
	global_load_dwordx4 v[136:139], v[128:129], off nt
	s_nop 0
	global_load_dwordx4 v[128:131], v[128:129], off offset:256 nt
	s_and_b64 vcc, exec, s[2:3]
	s_mov_b32 s30, s14
	s_mov_b32 s22, s16
	s_mov_b64 s[26:27], s[20:21]
	s_mov_b64 s[24:25], s[18:19]
	v_readlane_b32 s65, v254, 22
	v_readlane_b32 s66, v254, 23
	v_readlane_b32 s67, v254, 24
	v_readlane_b32 s70, v254, 27
	v_readlane_b32 s71, v254, 28
	v_readlane_b32 s72, v254, 29
	v_readlane_b32 s73, v254, 30
	v_readlane_b32 s74, v254, 31
	v_readlane_b32 s75, v254, 32
	v_readlane_b32 s76, v254, 33
	v_readlane_b32 s77, v254, 34
	v_readlane_b32 s78, v254, 35
	v_readlane_b32 s79, v254, 36
	s_waitcnt vmcnt(0)
	v_cvt_f32_f16_e32 v250, v246
	v_cvt_f32_f16_sdwa v251, v246 dst_sel:DWORD dst_unused:UNUSED_PAD src0_sel:WORD_1
	v_pk_fma_f32 v[160:161], v[160:161], v[116:117], v[250:251]
	s_nop 0
	v_cvt_pk_f16_f32 v246, v160, v161
	v_cvt_f32_f16_e32 v160, v248
	v_cvt_f32_f16_sdwa v161, v248 dst_sel:DWORD dst_unused:UNUSED_PAD src0_sel:WORD_1
	v_pk_fma_f32 v[156:157], v[156:157], v[108:109], v[160:161]
	s_nop 0
	v_cvt_pk_f16_f32 v248, v156, v157
	v_cvt_f32_f16_e32 v156, v247
	v_cvt_f32_f16_sdwa v157, v247 dst_sel:DWORD dst_unused:UNUSED_PAD src0_sel:WORD_1
	v_pk_fma_f32 v[156:157], v[162:163], v[118:119], v[156:157]
	s_nop 0
	v_cvt_pk_f16_f32 v247, v156, v157
	v_cvt_f32_f16_e32 v156, v249
	v_cvt_f32_f16_sdwa v157, v249 dst_sel:DWORD dst_unused:UNUSED_PAD src0_sel:WORD_1
	v_pk_fma_f32 v[156:157], v[158:159], v[110:111], v[156:157]
	s_nop 0
	v_cvt_pk_f16_f32 v249, v156, v157
	v_lshl_add_u64 v[156:157], s[56:57], 0, v[236:237]
	v_lshl_add_u64 v[160:161], v[156:157], 0, v[220:221]
	v_cvt_f32_f16_e32 v156, v200
	v_cvt_f32_f16_sdwa v157, v200 dst_sel:DWORD dst_unused:UNUSED_PAD src0_sel:WORD_1
	global_store_dwordx4 v[160:161], v[246:249], off
	v_pk_fma_f32 v[140:141], v[140:141], v[96:97], v[156:157]
	s_nop 0
	v_cvt_pk_f16_f32 v156, v140, v141
	v_cvt_f32_f16_e32 v140, v202
	v_cvt_f32_f16_sdwa v141, v202 dst_sel:DWORD dst_unused:UNUSED_PAD src0_sel:WORD_1
	v_pk_fma_f32 v[132:133], v[132:133], v[88:89], v[140:141]
	s_nop 0
	v_cvt_pk_f16_f32 v158, v132, v133
	v_cvt_f32_f16_e32 v132, v201
	v_cvt_f32_f16_sdwa v133, v201 dst_sel:DWORD dst_unused:UNUSED_PAD src0_sel:WORD_1
	v_pk_fma_f32 v[132:133], v[142:143], v[98:99], v[132:133]
	s_nop 0
	v_cvt_pk_f16_f32 v157, v132, v133
	v_cvt_f32_f16_e32 v132, v203
	v_cvt_f32_f16_sdwa v133, v203 dst_sel:DWORD dst_unused:UNUSED_PAD src0_sel:WORD_1
	v_pk_fma_f32 v[132:133], v[134:135], v[90:91], v[132:133]
	s_nop 0
	v_cvt_pk_f16_f32 v159, v132, v133
	v_cvt_f32_f16_e32 v132, v196
	v_cvt_f32_f16_sdwa v133, v196 dst_sel:DWORD dst_unused:UNUSED_PAD src0_sel:WORD_1
	global_store_dwordx4 v[160:161], v[156:159], off offset:256
	v_pk_fma_f32 v[124:125], v[124:125], v[116:117], v[132:133]
	s_nop 0
	v_cvt_pk_f16_f32 v132, v124, v125
	v_cvt_f32_f16_e32 v124, v198
	v_cvt_f32_f16_sdwa v125, v198 dst_sel:DWORD dst_unused:UNUSED_PAD src0_sel:WORD_1
	v_pk_fma_f32 v[120:121], v[120:121], v[108:109], v[124:125]
	s_nop 0
	v_cvt_pk_f16_f32 v134, v120, v121
	v_cvt_f32_f16_e32 v120, v197
	v_cvt_f32_f16_sdwa v121, v197 dst_sel:DWORD dst_unused:UNUSED_PAD src0_sel:WORD_1
	v_pk_fma_f32 v[120:121], v[126:127], v[118:119], v[120:121]
	s_nop 0
	v_cvt_pk_f16_f32 v133, v120, v121
	v_cvt_f32_f16_e32 v120, v199
	v_cvt_f32_f16_sdwa v121, v199 dst_sel:DWORD dst_unused:UNUSED_PAD src0_sel:WORD_1
	v_pk_fma_f32 v[120:121], v[122:123], v[110:111], v[120:121]
	s_nop 0
	v_cvt_pk_f16_f32 v135, v120, v121
	v_lshl_add_u64 v[120:121], s[56:57], 0, v[234:235]
	v_lshl_add_u64 v[124:125], v[120:121], 0, v[220:221]
	v_cvt_f32_f16_e32 v120, v192
	v_cvt_f32_f16_sdwa v121, v192 dst_sel:DWORD dst_unused:UNUSED_PAD src0_sel:WORD_1
	global_store_dwordx4 v[124:125], v[132:135], off
	v_pk_fma_f32 v[112:113], v[112:113], v[96:97], v[120:121]
	s_nop 0
	v_cvt_pk_f16_f32 v120, v112, v113
	v_cvt_f32_f16_e32 v112, v194
	v_cvt_f32_f16_sdwa v113, v194 dst_sel:DWORD dst_unused:UNUSED_PAD src0_sel:WORD_1
	v_pk_fma_f32 v[104:105], v[104:105], v[88:89], v[112:113]
	s_nop 0
	v_cvt_pk_f16_f32 v122, v104, v105
	v_cvt_f32_f16_e32 v104, v193
	v_cvt_f32_f16_sdwa v105, v193 dst_sel:DWORD dst_unused:UNUSED_PAD src0_sel:WORD_1
	v_pk_fma_f32 v[104:105], v[114:115], v[98:99], v[104:105]
	s_nop 0
	v_cvt_pk_f16_f32 v121, v104, v105
	v_cvt_f32_f16_e32 v104, v195
	v_cvt_f32_f16_sdwa v105, v195 dst_sel:DWORD dst_unused:UNUSED_PAD src0_sel:WORD_1
	v_pk_fma_f32 v[104:105], v[106:107], v[90:91], v[104:105]
	s_nop 0
	v_cvt_pk_f16_f32 v123, v104, v105
	v_cvt_f32_f16_e32 v104, v188
	v_cvt_f32_f16_sdwa v105, v188 dst_sel:DWORD dst_unused:UNUSED_PAD src0_sel:WORD_1
	global_store_dwordx4 v[124:125], v[120:123], off offset:256
	v_pk_fma_f32 v[100:101], v[100:101], v[116:117], v[104:105]
	s_nop 0
	v_cvt_pk_f16_f32 v104, v100, v101
	v_cvt_f32_f16_e32 v100, v190
	v_cvt_f32_f16_sdwa v101, v190 dst_sel:DWORD dst_unused:UNUSED_PAD src0_sel:WORD_1
	v_pk_fma_f32 v[92:93], v[92:93], v[108:109], v[100:101]
	s_nop 0
	v_cvt_pk_f16_f32 v106, v92, v93
	v_cvt_f32_f16_e32 v92, v189
	v_cvt_f32_f16_sdwa v93, v189 dst_sel:DWORD dst_unused:UNUSED_PAD src0_sel:WORD_1
	v_pk_fma_f32 v[92:93], v[102:103], v[118:119], v[92:93]
	s_nop 0
	v_cvt_pk_f16_f32 v105, v92, v93
	v_cvt_f32_f16_e32 v92, v191
	v_cvt_f32_f16_sdwa v93, v191 dst_sel:DWORD dst_unused:UNUSED_PAD src0_sel:WORD_1
	v_pk_fma_f32 v[92:93], v[94:95], v[110:111], v[92:93]
	s_nop 0
	v_cvt_pk_f16_f32 v107, v92, v93
	v_lshl_add_u64 v[92:93], s[56:57], 0, v[232:233]
	v_lshl_add_u64 v[100:101], v[92:93], 0, v[220:221]
	v_cvt_f32_f16_e32 v92, v184
	v_cvt_f32_f16_sdwa v93, v184 dst_sel:DWORD dst_unused:UNUSED_PAD src0_sel:WORD_1
	global_store_dwordx4 v[100:101], v[104:107], off
	v_pk_fma_f32 v[84:85], v[84:85], v[96:97], v[92:93]
	s_nop 0
	v_cvt_pk_f16_f32 v92, v84, v85
	v_cvt_f32_f16_e32 v84, v186
	v_cvt_f32_f16_sdwa v85, v186 dst_sel:DWORD dst_unused:UNUSED_PAD src0_sel:WORD_1
	v_pk_fma_f32 v[80:81], v[80:81], v[88:89], v[84:85]
	s_nop 0
	v_cvt_pk_f16_f32 v94, v80, v81
	v_cvt_f32_f16_e32 v80, v185
	v_cvt_f32_f16_sdwa v81, v185 dst_sel:DWORD dst_unused:UNUSED_PAD src0_sel:WORD_1
	v_pk_fma_f32 v[80:81], v[86:87], v[98:99], v[80:81]
	s_nop 0
	v_cvt_pk_f16_f32 v93, v80, v81
	v_cvt_f32_f16_e32 v80, v187
	v_cvt_f32_f16_sdwa v81, v187 dst_sel:DWORD dst_unused:UNUSED_PAD src0_sel:WORD_1
	v_pk_fma_f32 v[80:81], v[82:83], v[90:91], v[80:81]
	s_nop 0
	v_cvt_pk_f16_f32 v95, v80, v81
	v_cvt_f32_f16_e32 v80, v180
	v_cvt_f32_f16_sdwa v81, v180 dst_sel:DWORD dst_unused:UNUSED_PAD src0_sel:WORD_1
	global_store_dwordx4 v[100:101], v[92:95], off offset:256
	v_pk_fma_f32 v[76:77], v[76:77], v[116:117], v[80:81]
	s_nop 0
	v_cvt_pk_f16_f32 v80, v76, v77
	v_cvt_f32_f16_e32 v76, v182
	v_cvt_f32_f16_sdwa v77, v182 dst_sel:DWORD dst_unused:UNUSED_PAD src0_sel:WORD_1
	v_pk_fma_f32 v[72:73], v[72:73], v[108:109], v[76:77]
	s_nop 0
	v_cvt_pk_f16_f32 v82, v72, v73
	v_cvt_f32_f16_e32 v72, v181
	v_cvt_f32_f16_sdwa v73, v181 dst_sel:DWORD dst_unused:UNUSED_PAD src0_sel:WORD_1
	v_pk_fma_f32 v[72:73], v[78:79], v[118:119], v[72:73]
	s_nop 0
	v_cvt_pk_f16_f32 v81, v72, v73
	v_cvt_f32_f16_e32 v72, v183
	v_cvt_f32_f16_sdwa v73, v183 dst_sel:DWORD dst_unused:UNUSED_PAD src0_sel:WORD_1
	v_pk_fma_f32 v[72:73], v[74:75], v[110:111], v[72:73]
	s_nop 0
	v_cvt_pk_f16_f32 v83, v72, v73
	v_lshl_add_u64 v[72:73], s[56:57], 0, v[230:231]
	v_lshl_add_u64 v[76:77], v[72:73], 0, v[220:221]
	v_cvt_f32_f16_e32 v72, v176
	v_cvt_f32_f16_sdwa v73, v176 dst_sel:DWORD dst_unused:UNUSED_PAD src0_sel:WORD_1
	global_store_dwordx4 v[76:77], v[80:83], off
	v_pk_fma_f32 v[68:69], v[68:69], v[96:97], v[72:73]
	s_nop 0
	v_cvt_pk_f16_f32 v72, v68, v69
	v_cvt_f32_f16_e32 v68, v178
	v_cvt_f32_f16_sdwa v69, v178 dst_sel:DWORD dst_unused:UNUSED_PAD src0_sel:WORD_1
	v_pk_fma_f32 v[64:65], v[64:65], v[88:89], v[68:69]
	s_nop 0
	v_cvt_pk_f16_f32 v74, v64, v65
	v_cvt_f32_f16_e32 v64, v177
	v_cvt_f32_f16_sdwa v65, v177 dst_sel:DWORD dst_unused:UNUSED_PAD src0_sel:WORD_1
	v_pk_fma_f32 v[64:65], v[70:71], v[98:99], v[64:65]
	s_nop 0
	v_cvt_pk_f16_f32 v73, v64, v65
	v_cvt_f32_f16_e32 v64, v179
	v_cvt_f32_f16_sdwa v65, v179 dst_sel:DWORD dst_unused:UNUSED_PAD src0_sel:WORD_1
	v_pk_fma_f32 v[64:65], v[66:67], v[90:91], v[64:65]
	s_nop 0
	v_cvt_pk_f16_f32 v75, v64, v65
	v_cvt_f32_f16_e32 v64, v172
	v_cvt_f32_f16_sdwa v65, v172 dst_sel:DWORD dst_unused:UNUSED_PAD src0_sel:WORD_1
	global_store_dwordx4 v[76:77], v[72:75], off offset:256
	v_pk_fma_f32 v[60:61], v[60:61], v[116:117], v[64:65]
	s_nop 0
	v_cvt_pk_f16_f32 v64, v60, v61
	v_cvt_f32_f16_e32 v60, v174
	v_cvt_f32_f16_sdwa v61, v174 dst_sel:DWORD dst_unused:UNUSED_PAD src0_sel:WORD_1
	v_pk_fma_f32 v[56:57], v[56:57], v[108:109], v[60:61]
	s_nop 0
	v_cvt_pk_f16_f32 v66, v56, v57
	v_cvt_f32_f16_e32 v56, v173
	v_cvt_f32_f16_sdwa v57, v173 dst_sel:DWORD dst_unused:UNUSED_PAD src0_sel:WORD_1
	v_pk_fma_f32 v[56:57], v[62:63], v[118:119], v[56:57]
	s_nop 0
	v_cvt_pk_f16_f32 v65, v56, v57
	v_cvt_f32_f16_e32 v56, v175
	v_cvt_f32_f16_sdwa v57, v175 dst_sel:DWORD dst_unused:UNUSED_PAD src0_sel:WORD_1
	v_pk_fma_f32 v[56:57], v[58:59], v[110:111], v[56:57]
	s_nop 0
	v_cvt_pk_f16_f32 v67, v56, v57
	v_lshl_add_u64 v[56:57], s[56:57], 0, v[228:229]
	v_lshl_add_u64 v[60:61], v[56:57], 0, v[220:221]
	v_cvt_f32_f16_e32 v56, v168
	v_cvt_f32_f16_sdwa v57, v168 dst_sel:DWORD dst_unused:UNUSED_PAD src0_sel:WORD_1
	global_store_dwordx4 v[60:61], v[64:67], off
	v_pk_fma_f32 v[52:53], v[52:53], v[96:97], v[56:57]
	s_nop 0
	v_cvt_pk_f16_f32 v56, v52, v53
	v_cvt_f32_f16_e32 v52, v170
	v_cvt_f32_f16_sdwa v53, v170 dst_sel:DWORD dst_unused:UNUSED_PAD src0_sel:WORD_1
	v_pk_fma_f32 v[48:49], v[48:49], v[88:89], v[52:53]
	s_nop 0
	v_cvt_pk_f16_f32 v58, v48, v49
	v_cvt_f32_f16_e32 v48, v169
	v_cvt_f32_f16_sdwa v49, v169 dst_sel:DWORD dst_unused:UNUSED_PAD src0_sel:WORD_1
	v_pk_fma_f32 v[48:49], v[54:55], v[98:99], v[48:49]
	s_nop 0
	v_cvt_pk_f16_f32 v57, v48, v49
	v_cvt_f32_f16_e32 v48, v171
	v_cvt_f32_f16_sdwa v49, v171 dst_sel:DWORD dst_unused:UNUSED_PAD src0_sel:WORD_1
	v_pk_fma_f32 v[48:49], v[50:51], v[90:91], v[48:49]
	s_nop 0
	v_cvt_pk_f16_f32 v59, v48, v49
	v_cvt_f32_f16_e32 v48, v164
	v_cvt_f32_f16_sdwa v49, v164 dst_sel:DWORD dst_unused:UNUSED_PAD src0_sel:WORD_1
	global_store_dwordx4 v[60:61], v[56:59], off offset:256
	v_pk_fma_f32 v[44:45], v[44:45], v[116:117], v[48:49]
	s_nop 0
	v_cvt_pk_f16_f32 v48, v44, v45
	v_cvt_f32_f16_e32 v44, v166
	v_cvt_f32_f16_sdwa v45, v166 dst_sel:DWORD dst_unused:UNUSED_PAD src0_sel:WORD_1
	v_pk_fma_f32 v[40:41], v[40:41], v[108:109], v[44:45]
	s_nop 0
	v_cvt_pk_f16_f32 v50, v40, v41
	v_cvt_f32_f16_e32 v40, v165
	v_cvt_f32_f16_sdwa v41, v165 dst_sel:DWORD dst_unused:UNUSED_PAD src0_sel:WORD_1
	v_pk_fma_f32 v[40:41], v[46:47], v[118:119], v[40:41]
	s_nop 0
	v_cvt_pk_f16_f32 v49, v40, v41
	v_cvt_f32_f16_e32 v40, v167
	v_cvt_f32_f16_sdwa v41, v167 dst_sel:DWORD dst_unused:UNUSED_PAD src0_sel:WORD_1
	v_pk_fma_f32 v[40:41], v[42:43], v[110:111], v[40:41]
	s_nop 0
	v_cvt_pk_f16_f32 v51, v40, v41
	v_lshl_add_u64 v[40:41], s[56:57], 0, v[226:227]
	v_lshl_add_u64 v[44:45], v[40:41], 0, v[220:221]
	v_cvt_f32_f16_e32 v40, v152
	v_cvt_f32_f16_sdwa v41, v152 dst_sel:DWORD dst_unused:UNUSED_PAD src0_sel:WORD_1
	global_store_dwordx4 v[44:45], v[48:51], off
	v_pk_fma_f32 v[36:37], v[36:37], v[96:97], v[40:41]
	s_nop 0
	v_cvt_pk_f16_f32 v40, v36, v37
	v_cvt_f32_f16_e32 v36, v154
	v_cvt_f32_f16_sdwa v37, v154 dst_sel:DWORD dst_unused:UNUSED_PAD src0_sel:WORD_1
	v_pk_fma_f32 v[32:33], v[32:33], v[88:89], v[36:37]
	s_nop 0
	v_cvt_pk_f16_f32 v42, v32, v33
	v_cvt_f32_f16_e32 v32, v153
	v_cvt_f32_f16_sdwa v33, v153 dst_sel:DWORD dst_unused:UNUSED_PAD src0_sel:WORD_1
	v_pk_fma_f32 v[32:33], v[38:39], v[98:99], v[32:33]
	s_nop 0
	v_cvt_pk_f16_f32 v41, v32, v33
	v_cvt_f32_f16_e32 v32, v155
	v_cvt_f32_f16_sdwa v33, v155 dst_sel:DWORD dst_unused:UNUSED_PAD src0_sel:WORD_1
	v_pk_fma_f32 v[32:33], v[34:35], v[90:91], v[32:33]
	s_nop 0
	v_cvt_pk_f16_f32 v43, v32, v33
	v_cvt_f32_f16_e32 v32, v148
	v_cvt_f32_f16_sdwa v33, v148 dst_sel:DWORD dst_unused:UNUSED_PAD src0_sel:WORD_1
	global_store_dwordx4 v[44:45], v[40:43], off offset:256
	v_pk_fma_f32 v[28:29], v[28:29], v[116:117], v[32:33]
	s_nop 0
	v_cvt_pk_f16_f32 v32, v28, v29
	v_cvt_f32_f16_e32 v28, v150
	v_cvt_f32_f16_sdwa v29, v150 dst_sel:DWORD dst_unused:UNUSED_PAD src0_sel:WORD_1
	v_pk_fma_f32 v[24:25], v[24:25], v[108:109], v[28:29]
	s_nop 0
	v_cvt_pk_f16_f32 v34, v24, v25
	v_cvt_f32_f16_e32 v24, v149
	v_cvt_f32_f16_sdwa v25, v149 dst_sel:DWORD dst_unused:UNUSED_PAD src0_sel:WORD_1
	v_pk_fma_f32 v[24:25], v[30:31], v[118:119], v[24:25]
	s_nop 0
	v_cvt_pk_f16_f32 v33, v24, v25
	v_cvt_f32_f16_e32 v24, v151
	v_cvt_f32_f16_sdwa v25, v151 dst_sel:DWORD dst_unused:UNUSED_PAD src0_sel:WORD_1
	v_pk_fma_f32 v[24:25], v[26:27], v[110:111], v[24:25]
	s_nop 0
	v_cvt_pk_f16_f32 v35, v24, v25
	v_lshl_add_u64 v[24:25], s[56:57], 0, v[224:225]
	v_lshl_add_u64 v[28:29], v[24:25], 0, v[220:221]
	v_cvt_f32_f16_e32 v24, v144
	v_cvt_f32_f16_sdwa v25, v144 dst_sel:DWORD dst_unused:UNUSED_PAD src0_sel:WORD_1
	global_store_dwordx4 v[28:29], v[32:35], off
	v_pk_fma_f32 v[20:21], v[20:21], v[96:97], v[24:25]
	s_nop 0
	v_cvt_pk_f16_f32 v24, v20, v21
	v_cvt_f32_f16_e32 v20, v146
	v_cvt_f32_f16_sdwa v21, v146 dst_sel:DWORD dst_unused:UNUSED_PAD src0_sel:WORD_1
	v_pk_fma_f32 v[16:17], v[16:17], v[88:89], v[20:21]
	s_nop 0
	v_cvt_pk_f16_f32 v26, v16, v17
	v_cvt_f32_f16_e32 v16, v145
	v_cvt_f32_f16_sdwa v17, v145 dst_sel:DWORD dst_unused:UNUSED_PAD src0_sel:WORD_1
	v_pk_fma_f32 v[16:17], v[22:23], v[98:99], v[16:17]
	s_nop 0
	v_cvt_pk_f16_f32 v25, v16, v17
	v_cvt_f32_f16_e32 v16, v147
	v_cvt_f32_f16_sdwa v17, v147 dst_sel:DWORD dst_unused:UNUSED_PAD src0_sel:WORD_1
	v_pk_fma_f32 v[16:17], v[18:19], v[90:91], v[16:17]
	s_nop 0
	v_cvt_pk_f16_f32 v27, v16, v17
	v_cvt_f32_f16_e32 v16, v136
	v_cvt_f32_f16_sdwa v17, v136 dst_sel:DWORD dst_unused:UNUSED_PAD src0_sel:WORD_1
	global_store_dwordx4 v[28:29], v[24:27], off offset:256
	v_pk_fma_f32 v[12:13], v[12:13], v[116:117], v[16:17]
	s_nop 0
	v_cvt_pk_f16_f32 v16, v12, v13
	v_cvt_f32_f16_e32 v12, v138
	v_cvt_f32_f16_sdwa v13, v138 dst_sel:DWORD dst_unused:UNUSED_PAD src0_sel:WORD_1
	v_pk_fma_f32 v[8:9], v[8:9], v[108:109], v[12:13]
	s_nop 0
	v_cvt_pk_f16_f32 v18, v8, v9
	v_cvt_f32_f16_e32 v8, v137
	v_cvt_f32_f16_sdwa v9, v137 dst_sel:DWORD dst_unused:UNUSED_PAD src0_sel:WORD_1
	v_pk_fma_f32 v[8:9], v[14:15], v[118:119], v[8:9]
	s_nop 0
	v_cvt_pk_f16_f32 v17, v8, v9
	v_cvt_f32_f16_e32 v8, v139
	v_cvt_f32_f16_sdwa v9, v139 dst_sel:DWORD dst_unused:UNUSED_PAD src0_sel:WORD_1
	v_pk_fma_f32 v[8:9], v[10:11], v[110:111], v[8:9]
	s_nop 0
	v_cvt_pk_f16_f32 v19, v8, v9
	v_lshl_add_u64 v[8:9], s[56:57], 0, v[222:223]
	v_lshl_add_u64 v[12:13], v[8:9], 0, v[220:221]
	v_cvt_f32_f16_e32 v8, v128
	v_cvt_f32_f16_sdwa v9, v128 dst_sel:DWORD dst_unused:UNUSED_PAD src0_sel:WORD_1
	global_store_dwordx4 v[12:13], v[16:19], off
	v_pk_fma_f32 v[4:5], v[4:5], v[96:97], v[8:9]
	s_nop 0
	v_cvt_pk_f16_f32 v8, v4, v5
	v_cvt_f32_f16_e32 v4, v130
	v_cvt_f32_f16_sdwa v5, v130 dst_sel:DWORD dst_unused:UNUSED_PAD src0_sel:WORD_1
	v_pk_fma_f32 v[0:1], v[0:1], v[88:89], v[4:5]
	s_nop 0
	v_cvt_pk_f16_f32 v10, v0, v1
	v_cvt_f32_f16_e32 v0, v129
	v_cvt_f32_f16_sdwa v1, v129 dst_sel:DWORD dst_unused:UNUSED_PAD src0_sel:WORD_1
	v_pk_fma_f32 v[0:1], v[6:7], v[98:99], v[0:1]
	s_nop 0
	v_cvt_pk_f16_f32 v9, v0, v1
	v_cvt_f32_f16_e32 v0, v131
	v_cvt_f32_f16_sdwa v1, v131 dst_sel:DWORD dst_unused:UNUSED_PAD src0_sel:WORD_1
	v_pk_fma_f32 v[0:1], v[2:3], v[90:91], v[0:1]
	s_nop 0
	v_cvt_pk_f16_f32 v11, v0, v1
	global_store_dwordx4 v[12:13], v[8:11], off offset:256
	s_cbranch_vccz .LBB0_1178
	s_waitcnt vmcnt(0)
	s_cmpk_gt_u32 s34, 0xff
	s_cbranch_scc1 .LBB0_1189
	s_barrier
